# nt policy also on the RG-LRU background conversion stream loads and the HGRN2-prep q/f loads
# baseline (speedup 1.0000x reference)
; #define HP_LOAD(U_) do { const int h_ = (U_) & 31, n_ = ((U_) >> 5) & 127, b_ = (U_) >> 12; const size_t r_ = (size_t)b_ * SEQ + (size_t)n_ * 64 + 8 * rg; \
;         _Pragma("unroll") for (int i = 0; i < 8; ++i) { qr[i] = *(const unsigned*)(a.proj + C_Q + h_ * 128 + 2 * c2 + (r_ + i) * N1); fr_[i] = *(const unsigned*)(a.proj + C_F + h_ * 128 + 2 * c2 + (r_ + i) * N1); } } while (0)
; DI void hgrn2_prep_all(Frame& F, const Mix0Args& a) {
;     ...
;     unsigned qc[8], fc[8];
; #pragma unroll
;     for (int i = 0; i < 8; ++i) { qc[i] = qr[i]; fc[i] = fr_[i]; }
;     if (U + F.G < 8192) HP_LOAD(U + F.G);
.LBB0_145:
	s_add_i32 s86, s80, s92
	s_cmpk_gt_i32 s86, 0x1fff
	s_cselect_b64 s[36:37], -1, 0
	s_and_b64 vcc, exec, s[36:37]
	s_waitcnt vmcnt(0)
	v_mov_b32_e32 v96, v9
	v_mov_b32_e32 v98, v7
	v_mov_b32_e32 v101, v3
	v_mov_b32_e32 v103, v2
	v_mov_b32_e32 v105, v6
	v_mov_b32_e32 v107, v5
	v_mov_b32_e32 v109, v4
	v_mov_b32_e32 v111, v8
	v_mov_b32_e32 v20, v99
	v_mov_b32_e32 v97, v95
	v_mov_b32_e32 v100, v94
	v_mov_b32_e32 v102, v93
	v_mov_b32_e32 v104, v92
	v_mov_b32_e32 v106, v91
	v_mov_b32_e32 v108, v90
	v_mov_b32_e32 v110, v89
	s_cbranch_vccnz .LBB0_147
	s_and_b32 s88, s78, 0x1fc0
	s_ashr_i32 s87, s86, 12
	v_or_b32_e32 v10, s88, v1
	s_ashr_i32 s90, s87, 31
	v_lshl_or_b32 v16, s87, 13, v10
	s_and_b32 s87, s82, 0xf80
	s_lshl_b32 s92, s87, 1
	v_lshl_add_u64 v[10:11], v[22:23], 0, s[92:93]
	v_lshl_add_u64 v[12:13], v[24:25], 0, s[92:93]
	s_mul_i32 s87, s90, 0xc000
	v_mad_u64_u32 v[14:15], s[88:89], v16, s42, 0
	v_add_u32_e32 v17, s87, v15
	v_mad_u64_u32 v[36:37], s[88:89], v16, s42, v[10:11]
	v_mad_u64_u32 v[38:39], s[88:89], v16, s42, v[12:13]
	v_or_b32_e32 v16, 0xc000, v14
	v_mad_i32_i24 v37, s90, v73, v37
	v_lshl_add_u64 v[40:41], v[10:11], 0, v[16:17]
	global_load_dword v20, v[36:37], off nt
	global_load_dword v97, v[40:41], off nt
	v_lshl_add_u64 v[40:41], v[12:13], 0, v[16:17]
	v_or_b32_e32 v16, 0x18000, v14
	v_lshl_add_u64 v[10:11], v[10:11], 0, v[16:17]
	v_mad_i32_i24 v39, s90, v73, v39
	global_load_dword v100, v[10:11], off nt
	v_lshl_add_u64 v[10:11], v[12:13], 0, v[16:17]
	s_mov_b32 s16, 0x24000
	global_load_dword v96, v[38:39], off nt
	global_load_dword v101, v[10:11], off nt
	v_add_co_u32_e32 v10, vcc, s16, v36
	global_load_dword v98, v[40:41], off nt
	s_nop 0
	v_addc_co_u32_e32 v11, vcc, 0, v37, vcc
	global_load_dword v102, v[10:11], off nt
	v_add_co_u32_e32 v10, vcc, s16, v38
	v_readlane_b32 s92, v253, 45
	s_nop 0
	v_addc_co_u32_e32 v11, vcc, 0, v39, vcc
	global_load_dword v103, v[10:11], off nt
	v_add_co_u32_e32 v10, vcc, s43, v36
	s_nop 1
	v_addc_co_u32_e32 v11, vcc, 0, v37, vcc
	global_load_dword v104, v[10:11], off nt
	v_add_co_u32_e32 v10, vcc, s43, v38
	s_nop 1
	v_addc_co_u32_e32 v11, vcc, 0, v39, vcc
	global_load_dword v105, v[10:11], off nt
	v_add_co_u32_e32 v10, vcc, s33, v36
	s_nop 1
	v_addc_co_u32_e32 v11, vcc, 0, v37, vcc
	global_load_dword v106, v[10:11], off nt
	v_add_co_u32_e32 v10, vcc, s33, v38
	s_nop 1
	v_addc_co_u32_e32 v11, vcc, 0, v39, vcc
	global_load_dword v107, v[10:11], off nt
	v_add_co_u32_e32 v10, vcc, 0x48000, v36
	s_nop 1
	v_addc_co_u32_e32 v11, vcc, 0, v37, vcc
	global_load_dword v108, v[10:11], off nt
	v_add_co_u32_e32 v10, vcc, 0x48000, v38
	s_nop 1
	v_addc_co_u32_e32 v11, vcc, 0, v39, vcc
	global_load_dword v109, v[10:11], off nt
	v_add_co_u32_e32 v10, vcc, 0x54000, v36
	s_nop 1
	v_addc_co_u32_e32 v11, vcc, 0, v37, vcc
	global_load_dword v110, v[10:11], off nt
	v_add_co_u32_e32 v10, vcc, 0x54000, v38
	s_nop 1
	v_addc_co_u32_e32 v11, vcc, 0, v39, vcc
	global_load_dword v111, v[10:11], off nt

; #define LAS __attribute__((address_space(3)))
; DI float bf2f(unsigned h) { return __uint_as_float(h << 16); }
; DI float fexp2(float x) { return __builtin_amdgcn_exp2f(x); }
; DI float fsigmoid(float x) { return frcp(1.0f + fexp2(-LOG2E * x)); }
; #define LDS_BAR() do { asm volatile("s_waitcnt lgkmcnt(0)" ::: "memory"); __builtin_amdgcn_s_barrier(); asm volatile("" ::: "memory"); } while (0)
; DI void cv_issue_q(const CvJob& j, int idx, int lane, f32x4 (&v)[4], int r0) {
;     const float* W; int K, N, item; bf16* WT; const float* ks; cv_decode(j, idx, W, K, N, WT, ks, item);
;     const int nblk = N / 64, kb = item / nblk, nb = item % nblk, k0 = 64 * kb, n0 = 64 * nb, q = lane >> 4, c16 = lane & 15;
;     const char* ub = (const char*)(W + (size_t)(k0 + r0) * N + n0);
;     const unsigned vo = (unsigned)((16 * q) * N + 4 * c16) * 4u;
; #pragma unroll
;     for (int i = 0; i < 4; ++i) v[i] = *(const f32x4*)(ub + (size_t)i * N * 4 + vo);
; DI void rglru_scan_unit(Frame& F, const Mix0Args& a, int u) {
;     ...
;         { bf16x8 xf[4], waf[4], wxf[4]; unsigned xcr[4];
; #pragma unroll
;           for (int ks = 0; ks < 4; ++ks) { xf[ks] = *(const LAS bf16x8*)(XCc + (l0_ + fr) * S128 + ks * 64 + fq * 16);
;               waf[ks] = *(const LAS bf16x8*)(WAT + (16 * jtile + fr) * S128 + ks * 64 + fq * 16); wxf[ks] = *(const LAS bf16x8*)(WXT + (16 * jtile + fr) * S128 + ks * 64 + fq * 16); }
; #pragma unroll
;           for (int r = 0; r < 4; ++r) xcr[r] = *(const LAS unsigned short*)(XCc + (l0_ + 4 * fq + r) * S128 + (qq * 32 + jj) * 2);
;           f32x4 R = zero4, I = zero4;
; #pragma unroll
;           for (int ks = 0; ks < 4; ++ks) { R = __builtin_amdgcn_mfma_f32_16x16x32_bf16(xf[ks], waf[ks], R, 0, 0, 0); I = __builtin_amdgcn_mfma_f32_16x16x32_bf16(xf[ks], wxf[ks], I, 0, 0, 0); }
; #pragma unroll
;           for (int r = 0; r < 4; ++r) {
;               const float rr = fsigmoid(R[r] + bav), ig = fsigmoid(I[r] + bxv);
;               const float aa = fexp2(-sp8l2 * rr); const float om = __builtin_fmaf(-aa, aa, 1.0f);
;               av[r] = aa; uv[r] = __builtin_sqrtf(om) * (ig * bf2f(xcr[r]));
;               Hseg = aa * Hseg + uv[r]; Aseg *= aa; } }
;         const int sgi = ltile * 4 + fq;
;         SEGA[jj * 20 + sgi] = Aseg; SEGH[jj * 20 + sgi] = Hseg;
;         LDS_BAR();
.LBB0_269:
	s_lshr_b32 s79, s78, 6
	v_cvt_f32_u32_e32 v2, s79
	s_sub_i32 s90, 0, s79
	s_abs_i32 s89, s84
	s_ashr_i32 s88, s84, 31
	v_rcp_iflag_f32_e32 v2, v2
	v_mul_u32_u24_e32 v29, s78, v102
	v_or_b32_e32 v29, v29, v125
	v_lshlrev_b32_e32 v82, 2, v29
	v_mul_f32_e32 v2, 0x4f7ffffe, v2
	v_cvt_u32_f32_e32 v2, v2
	ds_read_b128 v[6:9], v103 offset:36864
	v_readfirstlane_b32 s91, v2
	s_mul_i32 s90, s90, s91
	s_mul_hi_u32 s90, s91, s90
	s_add_i32 s91, s91, s90
	s_mul_hi_u32 s90, s89, s91
	s_mul_i32 s91, s90, s79
	s_sub_i32 s89, s89, s91
	s_add_i32 vcc_lo, s90, 1
	s_sub_i32 s91, s89, s79
	s_cmp_ge_u32 s89, s79
	s_cselect_b32 s90, vcc_lo, s90
	s_cselect_b32 s89, s91, s89
	s_add_i32 s91, s90, 1
	ds_read_b128 v[2:5], v164
	s_cmp_ge_u32 s89, s79
	s_cselect_b32 s89, s91, s90
	s_xor_b32 s89, s89, s88
	s_sub_i32 s88, s89, s88
	s_mul_i32 s79, s88, s79
	s_lshl_b32 s88, s88, 6
	s_sub_i32 s79, s84, s79
	s_mul_hi_i32 s89, s88, s78
	s_mul_i32 s88, s88, s78
	s_lshl_b32 s90, s79, 6
	s_lshl_b64 s[88:89], s[88:89], 2
	s_add_u32 s79, s36, s88
	ds_read_b128 v[10:13], v103 offset:46080
	ds_read_b128 v[14:17], v164 offset:64
	ds_read_b128 v[30:33], v103 offset:36928
	ds_read_b128 v[38:41], v103 offset:46144
	ds_read_b128 v[42:45], v164 offset:128
	s_addc_u32 s84, s37, s89
	s_ashr_i32 s91, s90, 31
	s_waitcnt lgkmcnt(5)
	v_mfma_f32_16x16x32_bf16 v[6:9], v[2:5], v[6:9], 0
	s_lshl_b64 s[36:37], s[90:91], 2
	s_add_u32 s36, s79, s36
	s_addc_u32 s37, s84, s37
	s_waitcnt lgkmcnt(4)
	v_mfma_f32_16x16x32_bf16 v[10:13], v[2:5], v[10:13], 0
	global_load_dwordx4 v[2:5], v82, s[36:37] nt
	s_lshl_b32 s96, s78, 2
	v_lshl_add_u64 v[54:55], s[36:37], 0, v[82:83]
	s_waitcnt lgkmcnt(2)
	v_mfma_f32_16x16x32_bf16 v[6:9], v[14:17], v[30:33], v[6:9]
	ds_read_b128 v[30:33], v103 offset:36992
	ds_read_b128 v[46:49], v164 offset:192
	s_waitcnt lgkmcnt(3)
	v_mfma_f32_16x16x32_bf16 v[14:17], v[14:17], v[38:41], v[10:13]
	ds_read_b128 v[38:41], v103 offset:37056
	s_waitcnt lgkmcnt(2)
	v_mfma_f32_16x16x32_bf16 v[30:33], v[42:45], v[30:33], v[6:9]
	v_lshl_add_u64 v[10:11], v[54:55], 0, s[96:97]
	v_lshl_add_u64 v[58:59], v[10:11], 0, s[96:97]
	s_nop 0
	global_load_dwordx4 v[6:9], v[10:11], off nt
	s_nop 0
	global_load_dwordx4 v[10:13], v[58:59], off nt
	s_waitcnt lgkmcnt(0)
	v_mfma_f32_16x16x32_bf16 v[30:33], v[46:49], v[38:41], v[30:33]
	ds_read_b128 v[54:57], v103 offset:46208
	ds_read_b128 v[38:41], v103 offset:46272
	v_lshl_add_u64 v[58:59], v[58:59], 0, s[96:97]
	s_waitcnt lgkmcnt(1)
	v_mfma_f32_16x16x32_bf16 v[42:45], v[42:45], v[54:57], v[14:17]
	s_nop 2
	v_add_f32_e32 v29, v165, v30
	v_mul_f32_e32 v29, 0xbfb8aa3b, v29
	v_exp_f32_e32 v29, v29
	s_waitcnt lgkmcnt(0)
	v_mfma_f32_16x16x32_bf16 v[38:41], v[46:49], v[38:41], v[42:45]
	v_add_f32_e32 v31, v165, v31
	v_mul_f32_e32 v31, 0xbfb8aa3b, v31
	v_add_f32_e32 v14, 1.0, v29
	v_rcp_f32_e32 v29, v14
	v_exp_f32_e32 v31, v31
	global_load_dwordx4 v[14:17], v[58:59], off nt
	ds_read_u16 v42, v113
	ds_read_u16 v43, v113 offset:288
	ds_read_u16 v44, v113 offset:576
	ds_read_u16 v45, v113 offset:864
	v_mul_f32_e64 v29, v29, -v168
	v_exp_f32_e32 v70, v29
	v_add_f32_e32 v29, v167, v38
	v_mul_f32_e32 v29, 0xbfb8aa3b, v29
	v_exp_f32_e32 v29, v29
	v_fma_f32 v30, -v70, v70, 1.0
	s_nop 0
	s_nop 0
	v_add_f32_e32 v29, 1.0, v29
	v_rcp_f32_e32 v29, v29
	s_nop 0
	v_sqrt_f32_e32 v38, v30
	v_add_f32_e32 v31, 1.0, v31
	v_rcp_f32_e32 v31, v31
	v_add_f32_e32 v32, v165, v32
	v_add_u32_e32 v46, -1, v38
	v_fma_f32 v47, -v46, v38, v30
	v_cmp_ge_f32_e64 s[36:37], 0, v47
	v_add_u32_e32 v47, 1, v38
	v_mul_f32_e32 v32, 0xbfb8aa3b, v32
	v_cndmask_b32_e64 v46, v38, v46, s[36:37]
	v_fma_f32 v38, -v47, v38, v30
	v_cmp_lt_f32_e64 s[36:37], 0, v38
	v_exp_f32_e32 v32, v32
	v_add_f32_e32 v33, v165, v33
	v_cndmask_b32_e64 v38, v46, v47, s[36:37]
	s_nop 0
	s_nop 0
	s_nop 0
	v_add_f32_e32 v32, 1.0, v32
	v_rcp_f32_e32 v32, v32
	v_mov_b32_e32 v30, v38
	s_waitcnt lgkmcnt(3)
	v_lshlrev_b32_e32 v38, 16, v42
	v_mul_f32_e32 v29, v29, v38
	v_mul_f32_e32 v71, v29, v30
	v_mul_f32_e64 v29, v31, -v168
	v_exp_f32_e32 v72, v29
	v_add_f32_e32 v29, v167, v39
	v_mul_f32_e32 v29, 0xbfb8aa3b, v29
	v_exp_f32_e32 v29, v29
	v_fma_f32 v30, -v72, v72, 1.0
	s_nop 0
	s_nop 0
	v_add_f32_e32 v29, 1.0, v29
	v_rcp_f32_e32 v29, v29
	s_nop 0
	v_sqrt_f32_e32 v31, v30
	v_mul_f32_e32 v33, 0xbfb8aa3b, v33
	v_exp_f32_e32 v33, v33
	v_fma_f32 v38, 0, v70, v71
	v_add_u32_e32 v39, -1, v31
	v_fma_f32 v42, -v39, v31, v30
	v_cmp_ge_f32_e64 s[36:37], 0, v42
	v_add_u32_e32 v42, 1, v31
	v_add_f32_e32 v33, 1.0, v33
	v_cndmask_b32_e64 v39, v31, v39, s[36:37]
	v_fma_f32 v31, -v42, v31, v30
	v_cmp_lt_f32_e64 s[36:37], 0, v31
	v_rcp_f32_e32 v33, v33
	s_nop 0
	v_cndmask_b32_e64 v31, v39, v42, s[36:37]
	s_nop 0
	s_nop 0
	s_nop 0
	s_nop 1
	v_mov_b32_e32 v30, v31
	s_waitcnt lgkmcnt(2)
	v_lshlrev_b32_e32 v31, 16, v43
	v_mul_f32_e32 v29, v29, v31
	v_mul_f32_e32 v73, v29, v30
	v_mul_f32_e64 v30, v32, -v168
	v_exp_f32_e32 v74, v30
	v_add_f32_e32 v30, v167, v40
	v_mul_f32_e32 v30, 0xbfb8aa3b, v30
	v_exp_f32_e32 v30, v30
	v_fma_f32 v31, -v74, v74, 1.0
	s_nop 0
	s_nop 0
	v_add_f32_e32 v30, 1.0, v30
	v_rcp_f32_e32 v30, v30
	s_nop 0
	v_sqrt_f32_e32 v32, v31
	v_fma_f32 v29, v72, v38, v73
	v_mul_f32_e32 v38, v70, v72
	v_add_u32_e32 v39, -1, v32
	v_fma_f32 v40, -v39, v32, v31
	v_cmp_ge_f32_e64 s[36:37], 0, v40
	v_add_u32_e32 v40, 1, v32
	s_nop 0
	v_cndmask_b32_e64 v39, v32, v39, s[36:37]
	v_fma_f32 v32, -v40, v32, v31
	v_cmp_lt_f32_e64 s[36:37], 0, v32
	s_nop 1
	v_cndmask_b32_e64 v32, v39, v40, s[36:37]
	s_nop 0
	s_nop 0
	s_nop 0
	s_nop 1
	v_mov_b32_e32 v31, v32
	s_waitcnt lgkmcnt(1)
	v_lshlrev_b32_e32 v32, 16, v44
	v_mul_f32_e32 v30, v30, v32
	v_mul_f32_e32 v75, v30, v31
	v_fma_f32 v30, v74, v29, v75
	v_mul_f32_e64 v29, v33, -v168
	v_exp_f32_e32 v76, v29
	v_add_f32_e32 v29, v167, v41
	v_mul_f32_e32 v29, 0xbfb8aa3b, v29
	v_exp_f32_e32 v29, v29
	v_fma_f32 v31, -v76, v76, 1.0
	s_nop 0
	s_nop 0
	v_mul_f32_e32 v33, v74, v38
	v_add_f32_e32 v29, 1.0, v29
	s_nop 0
	v_sqrt_f32_e32 v32, v31
	v_rcp_f32_e32 v29, v29
	v_add_u32_e32 v38, -1, v32
	v_fma_f32 v39, -v38, v32, v31
	v_cmp_ge_f32_e64 s[36:37], 0, v39
	v_add_u32_e32 v39, 1, v32
	s_nop 0
	v_cndmask_b32_e64 v38, v32, v38, s[36:37]
	v_fma_f32 v32, -v39, v32, v31
	v_cmp_lt_f32_e64 s[36:37], 0, v32
	s_nop 1
	v_cndmask_b32_e64 v32, v38, v39, s[36:37]
	s_nop 0
	s_nop 0
	s_nop 0
	s_mov_b32 s36, 0x25300000
	s_nop 0
	v_mov_b32_e32 v31, v32
	s_waitcnt lgkmcnt(0)
	v_lshlrev_b32_e32 v32, 16, v45
	v_mul_f32_e32 v29, v29, v32
	v_mul_f32_e32 v29, v29, v31
	v_fma_f32 v30, v76, v30, v29
	v_mul_f32_e32 v31, v76, v33
	ds_write2st64_b32 v150, v31, v30 offset0:216 offset1:226
	s_waitcnt lgkmcnt(0)
	s_barrier
; #define LAS __attribute__((address_space(3)))
; DI float bf2f(unsigned h) { return __uint_as_float(h << 16); }
; DI unsigned pk2(float lo, float hi) { f32x2 v = {lo, hi}; bf16v2 b = __builtin_convertvector(v, bf16v2); return __builtin_bit_cast(unsigned, b); }
; DI float fsilu(float x) { return x * fsigmoid(x); }
; DI void rglru_scan_unit(Frame& F, const Mix0Args& a, int u) {
;     ...
;         float carry = HPREV[jj * 20 + (n & 1)]; float sa[15], sh[15];
;         { f32x4 a4[4], h4[4];
; #pragma unroll
;           for (int i = 0; i < 4; ++i) { a4[i] = *(const LAS f32x4*)(SEGA + jj * 20 + 4 * i); h4[i] = *(const LAS f32x4*)(SEGH + jj * 20 + 4 * i); }
; #pragma unroll
;           for (int s = 0; s < 15; ++s) { sa[s] = a4[s >> 2][s & 3]; sh[s] = h4[s >> 2][s & 3]; } }
; #pragma unroll
;         for (int s = 0; s < 15; ++s) carry = (s < sgi) ? sa[s] * carry + sh[s] : carry;
; #pragma unroll
;         for (int r = 0; r < 4; ++r) { carry = av[r] * carry + uv[r];
;             const float o = carry * fsilu(bf2f(gb_cur[r]));
;             obcol[(row0 + l0_ + 4 * fq + r) * a.out_ld] = (bf16)(pk2(o, 0.f) & 0xffffu); }
;         if (sgi == 15) HPREV[jj * 20 + ((n + 1) & 1)] = carry;
	ds_read_b32 v77, v149 offset:55360
	ds_read_b128 v[30:33], v149 offset:57856
	ds_read_b128 v[38:41], v149 offset:57872
	ds_read_b128 v[42:45], v149 offset:57888
	ds_read_b128 v[46:49], v149 offset:55296
	ds_read_b128 v[54:57], v149 offset:55312
	ds_read_b128 v[58:61], v149 offset:55328
	ds_read_b128 v[62:65], v149 offset:55344
	ds_read_b128 v[66:69], v149 offset:57904
	s_waitcnt lgkmcnt(4)
	v_fma_f32 v30, v77, v46, v30
	v_cndmask_b32_e64 v30, v30, v77, s[10:11]
	v_fma_f32 v31, v47, v30, v31
	v_cndmask_b32_e64 v30, v30, v31, s[12:13]
	v_fma_f32 v31, v48, v30, v32
	v_cndmask_b32_e64 v30, v30, v31, s[14:15]
	v_fmac_f32_e32 v33, v49, v30
	v_cndmask_b32_e64 v30, v33, v30, s[0:1]
	s_waitcnt lgkmcnt(3)
	v_fma_f32 v31, v54, v30, v38
	v_cndmask_b32_e64 v30, v30, v31, s[16:17]
	v_fma_f32 v31, v55, v30, v39
	v_cndmask_b32_e64 v30, v30, v31, s[18:19]
	v_fma_f32 v31, v56, v30, v40
	v_cndmask_b32_e64 v30, v30, v31, s[20:21]
	v_fmac_f32_e32 v41, v57, v30
	v_cndmask_b32_e64 v30, v30, v41, s[38:39]
	s_waitcnt lgkmcnt(2)
	v_fma_f32 v31, v58, v30, v42
	v_cndmask_b32_e64 v30, v30, v31, s[22:23]
	v_fma_f32 v31, v59, v30, v43
	v_cndmask_b32_e64 v30, v30, v31, s[24:25]
	v_fma_f32 v31, v60, v30, v44
	v_cndmask_b32_e64 v30, v30, v31, s[26:27]
	v_lshlrev_b32_e32 v32, 16, v181
	v_fmac_f32_e32 v45, v61, v30
	v_mul_f32_e32 v33, 0xbfb8aa3b, v32
	v_cndmask_b32_e64 v30, v30, v45, s[4:5]
	v_exp_f32_e32 v33, v33
	s_waitcnt lgkmcnt(0)
	v_fma_f32 v31, v62, v30, v66
	v_cndmask_b32_e64 v30, v30, v31, s[28:29]
	v_fma_f32 v31, v63, v30, v67
	v_cndmask_b32_e64 v30, v30, v31, s[30:31]
	v_add_f32_e32 v31, 1.0, v33
	v_rcp_f32_e32 v31, v31
	v_fmac_f32_e32 v68, v64, v30
	v_cndmask_b32_e64 v30, v30, v68, s[34:35]
	v_fmac_f32_e32 v71, v70, v30
	v_mul_f32_e32 v30, v31, v32
	v_mul_f32_e32 v30, v30, v71
	v_lshlrev_b32_e32 v33, 16, v180
	v_cvt_pk_bf16_f32 v32, v30, s0
	v_mul_f32_e32 v30, 0xbfb8aa3b, v33
	v_exp_f32_e32 v38, v30
	v_lshl_add_u64 v[66:67], v[116:117], 0, s[8:9]
	v_add_co_u32_e32 v30, vcc, s36, v66
	v_fmac_f32_e32 v73, v72, v71
	s_nop 0
	v_addc_co_u32_e32 v31, vcc, 0, v67, vcc
	global_store_short v[30:31], v32, off
	v_add_f32_e32 v30, 1.0, v38
	v_rcp_f32_e32 v30, v30
	v_lshlrev_b32_e32 v32, 16, v179
	v_mul_f32_e32 v31, 0xbfb8aa3b, v32
	v_exp_f32_e32 v31, v31
	v_mul_f32_e32 v30, v30, v33
	v_mul_f32_e32 v30, v30, v73
	v_cvt_pk_bf16_f32 v33, v30, s0
	v_add_f32_e32 v30, 1.0, v31
	v_rcp_f32_e32 v38, v30
	s_mov_b32 s36, 0x2530c000
	v_add_co_u32_e32 v30, vcc, s36, v66
	v_fmac_f32_e32 v75, v74, v73
	s_nop 0
	v_addc_co_u32_e32 v31, vcc, 0, v67, vcc
	global_store_short v[30:31], v33, off
	v_mul_f32_e32 v30, v38, v32
	v_lshlrev_b32_e32 v32, 16, v178
	v_mul_f32_e32 v31, 0xbfb8aa3b, v32
	v_exp_f32_e32 v31, v31
	v_mul_f32_e32 v30, v30, v75
	s_mov_b32 s36, 0x25318000
	v_cvt_pk_bf16_f32 v33, v30, s0
	v_add_f32_e32 v31, 1.0, v31
	v_rcp_f32_e32 v38, v31
	v_add_co_u32_e32 v30, vcc, s36, v66
	v_fmac_f32_e32 v29, v76, v75
	s_nop 0
	v_addc_co_u32_e32 v31, vcc, 0, v67, vcc
	global_store_short v[30:31], v33, off
	v_mul_f32_e32 v30, v38, v32
	v_mul_f32_e32 v30, v30, v29
	v_cvt_pk_bf16_f32 v32, v30, s0
	s_mov_b64 s[100:101], 0x25324000
	v_lshl_add_u64 v[30:31], v[66:67], 0, s[100:101]
	global_store_short v[30:31], v32, off
	s_and_saveexec_b64 s[36:37], s[34:35]
	ds_write_b32 v149, v29 offset:55364
	s_or_b64 exec, exec, s[36:37]
	s_waitcnt vmcnt(22)
	v_lshlrev_b32_e32 v30, 16, v18
	v_and_b32_e32 v31, 0xffff0000, v18
	v_pk_fma_f32 v[30:31], v[104:105], v[30:31], v[100:101]
	s_waitcnt vmcnt(21)
	v_lshlrev_b32_e32 v18, 16, v19
	v_and_b32_e32 v19, 0xffff0000, v19
	v_pk_fma_f32 v[30:31], v[106:107], v[18:19], v[30:31]
	s_waitcnt vmcnt(20)
	v_lshlrev_b32_e32 v32, 16, v20
	v_and_b32_e32 v33, 0xffff0000, v20
	v_pk_fma_f32 v[30:31], v[108:109], v[32:33], v[30:31]
	s_waitcnt vmcnt(19)
	v_lshlrev_b32_e32 v20, 16, v21
	v_and_b32_e32 v21, 0xffff0000, v21
	v_pk_fma_f32 v[18:19], v[104:105], v[18:19], v[100:101]
	v_pk_fma_f32 v[30:31], v[110:111], v[20:21], v[30:31]
	v_pk_fma_f32 v[18:19], v[106:107], v[32:33], v[18:19]
	v_cvt_pk_bf16_f32 v29, v30, v31
	v_pk_fma_f32 v[18:19], v[108:109], v[20:21], v[18:19]
	s_waitcnt vmcnt(18)
	v_lshlrev_b32_e32 v30, 16, v22
	v_and_b32_e32 v31, 0xffff0000, v22
	v_pk_fma_f32 v[18:19], v[110:111], v[30:31], v[18:19]
	s_waitcnt vmcnt(17)
	v_lshlrev_b32_e32 v22, 16, v23
	v_cvt_pk_bf16_f32 v18, v18, v19
	ds_write2_b32 v123, v29, v18 offset1:72
	v_pk_fma_f32 v[18:19], v[104:105], v[32:33], v[100:101]
	v_and_b32_e32 v23, 0xffff0000, v23
	v_pk_fma_f32 v[18:19], v[106:107], v[20:21], v[18:19]
	v_add_u32_e32 v54, 0x400, v123
	v_pk_fma_f32 v[18:19], v[108:109], v[30:31], v[18:19]
	s_mov_b32 s36, 0x25be4000
	v_pk_fma_f32 v[18:19], v[110:111], v[22:23], v[18:19]
	s_nop 0
	v_cvt_pk_bf16_f32 v29, v18, v19
	v_pk_fma_f32 v[18:19], v[104:105], v[20:21], v[100:101]
	s_waitcnt vmcnt(16)
; DI void cv_decode(const CvJob& j, int idx, const float*& W, int& K, int& N, bf16*& WT, const float*& ks, int& item) {
;     if (idx < CV_I2) { W = j.e_w_out; K = K2; N = D; WT = j.W2; ks = nullptr; item = idx; }
;     else if (idx < CV_I2 + CV_I3) { W = j.o_w_in; K = D; N = N3; WT = j.W3; ks = j.kscale3; item = idx - CV_I2; }
;     else { W = j.o_w_out; K = K4; N = D; WT = j.W4; ks = j.kscale4; item = idx - CV_I2 - CV_I3; }
; }
	v_lshlrev_b32_e32 v20, 16, v24
	v_pk_fma_f32 v[18:19], v[106:107], v[30:31], v[18:19]
	v_and_b32_e32 v21, 0xffff0000, v24
	v_pk_fma_f32 v[18:19], v[108:109], v[22:23], v[18:19]
	s_nop 0
	v_pk_fma_f32 v[18:19], v[110:111], v[20:21], v[18:19]
	s_nop 0
	v_cvt_pk_bf16_f32 v18, v18, v19
	ds_write2_b32 v123, v29, v18 offset0:144 offset1:216
	v_pk_fma_f32 v[18:19], v[104:105], v[30:31], v[100:101]
	s_waitcnt vmcnt(15)
	v_lshlrev_b32_e32 v30, 16, v27
	v_pk_fma_f32 v[18:19], v[106:107], v[22:23], v[18:19]
	v_and_b32_e32 v31, 0xffff0000, v27
	v_pk_fma_f32 v[18:19], v[108:109], v[20:21], v[18:19]
	s_nop 0
	v_pk_fma_f32 v[18:19], v[110:111], v[30:31], v[18:19]
	s_nop 0
	v_cvt_pk_bf16_f32 v24, v18, v19
	v_pk_fma_f32 v[18:19], v[104:105], v[22:23], v[100:101]
	s_waitcnt vmcnt(14)
	v_lshlrev_b32_e32 v22, 16, v25
	v_pk_fma_f32 v[18:19], v[106:107], v[20:21], v[18:19]
	v_and_b32_e32 v23, 0xffff0000, v25
	v_pk_fma_f32 v[18:19], v[108:109], v[30:31], v[18:19]
	s_nop 0
	v_pk_fma_f32 v[18:19], v[110:111], v[22:23], v[18:19]
	s_nop 0
	v_cvt_pk_bf16_f32 v18, v18, v19
	ds_write2_b32 v54, v24, v18 offset0:32 offset1:104
	v_pk_fma_f32 v[18:19], v[104:105], v[20:21], v[100:101]
	s_waitcnt vmcnt(13)
	v_lshlrev_b32_e32 v20, 16, v26
	v_pk_fma_f32 v[18:19], v[106:107], v[30:31], v[18:19]
	v_and_b32_e32 v21, 0xffff0000, v26
	v_pk_fma_f32 v[18:19], v[108:109], v[22:23], v[18:19]
	s_nop 0
	v_pk_fma_f32 v[18:19], v[110:111], v[20:21], v[18:19]
	s_nop 0
	v_cvt_pk_bf16_f32 v24, v18, v19
	v_pk_fma_f32 v[18:19], v[104:105], v[30:31], v[100:101]
	s_nop 0
	v_pk_fma_f32 v[18:19], v[106:107], v[22:23], v[18:19]
	s_nop 0
	v_pk_fma_f32 v[18:19], v[108:109], v[20:21], v[18:19]
	s_waitcnt vmcnt(12)
	v_lshlrev_b32_e32 v20, 16, v28
	v_and_b32_e32 v21, 0xffff0000, v28
	v_pk_fma_f32 v[18:19], v[110:111], v[20:21], v[18:19]
	s_nop 0
	v_cvt_pk_bf16_f32 v18, v18, v19
	ds_write2_b32 v54, v24, v18 offset0:176 offset1:248
	v_add_co_u32_e32 v18, vcc, s36, v50
	s_mov_b32 s36, 0x25bf0000
	s_nop 0
	v_addc_co_u32_e32 v19, vcc, 0, v51, vcc
	global_load_dword v130, v[18:19], off
	v_add_co_u32_e32 v18, vcc, s36, v50
	s_mov_b32 s36, 0x25bfc000
	s_nop 0
	v_addc_co_u32_e32 v19, vcc, 0, v51, vcc
	global_load_dword v132, v[18:19], off
	v_add_co_u32_e32 v18, vcc, s36, v50
	s_mov_b32 s36, 0x25c08000
	s_nop 0
	v_addc_co_u32_e32 v19, vcc, 0, v51, vcc
	global_load_dword v134, v[18:19], off
	v_add_co_u32_e32 v18, vcc, s36, v50
	s_mov_b32 s36, 0x25c14000
	s_nop 0
	v_addc_co_u32_e32 v19, vcc, 0, v51, vcc
	global_load_dword v169, v[18:19], off
	v_add_co_u32_e32 v18, vcc, s36, v50
	s_mov_b32 s36, 0x25c20000
	s_nop 0
	v_addc_co_u32_e32 v19, vcc, 0, v51, vcc
	global_load_dword v170, v[18:19], off
	v_add_co_u32_e32 v18, vcc, s36, v50
	s_mov_b32 s36, 0x25c2c000
	s_nop 0
	v_addc_co_u32_e32 v19, vcc, 0, v51, vcc
	global_load_dword v171, v[18:19], off
	v_add_co_u32_e32 v18, vcc, s36, v50
	s_mov_b32 s36, 0x25c38000
	s_nop 0
	v_addc_co_u32_e32 v19, vcc, 0, v51, vcc
	global_load_dword v172, v[18:19], off
	v_add_co_u32_e32 v18, vcc, s36, v50
	s_mov_b32 s36, 0x25c44000
	s_nop 0
	v_addc_co_u32_e32 v19, vcc, 0, v51, vcc
	global_load_dword v173, v[18:19], off
	v_add_co_u32_e32 v18, vcc, s36, v50
	s_mov_b32 s36, 0x25c50000
	s_nop 0
	v_addc_co_u32_e32 v19, vcc, 0, v51, vcc
	global_load_dword v174, v[18:19], off
	v_add_co_u32_e32 v18, vcc, s36, v50
	s_mov_b32 s36, 0x25c5c000
	s_nop 0
	v_addc_co_u32_e32 v19, vcc, 0, v51, vcc
	global_load_dword v175, v[18:19], off
	v_add_co_u32_e32 v18, vcc, s36, v50
	s_mov_b32 s36, 0x2590a000
	s_nop 0
	v_addc_co_u32_e32 v19, vcc, 0, v51, vcc
	global_load_dword v176, v[18:19], off
	v_add_co_u32_e32 v18, vcc, s36, v52
	s_nop 1
	v_addc_co_u32_e32 v19, vcc, 0, v53, vcc
	global_load_ushort v58, v[18:19], off
	s_mov_b64 s[100:101], 0x25916000
	v_lshl_add_u64 v[18:19], v[52:53], 0, s[100:101]
	global_load_ushort v56, v[18:19], off
	s_mov_b64 s[100:101], 0x25922000
	v_lshl_add_u64 v[18:19], v[52:53], 0, s[100:101]
	global_load_ushort v55, v[18:19], off
	s_mov_b64 s[100:101], 0x2592e000
	v_lshl_add_u64 v[18:19], v[52:53], 0, s[100:101]
	global_load_ushort v57, v[18:19], off
	v_cndmask_b32_e64 v18, 0, 1, s[40:41]
	v_cmp_ne_u32_e64 s[36:37], 1, v18
	s_andn2_b64 vcc, exec, s[40:41]
	s_cbranch_vccnz .LBB0_274
	s_cmpk_gt_u32 s87, 0x687f
	s_cbranch_scc0 .LBB0_275
	s_add_i32 s84, s87, 0xffff9780
	s_mov_b64 s[40:41], s[52:53]
	s_movk_i32 s78, 0x1000
	s_cbranch_execz .LBB0_276
	s_branch .LBB0_277

; #define LAS __attribute__((address_space(3)))
; DI float bf2f(unsigned h) { return __uint_as_float(h << 16); }
; DI float fexp2(float x) { return __builtin_amdgcn_exp2f(x); }
; DI float fsigmoid(float x) { return frcp(1.0f + fexp2(-LOG2E * x)); }
; #define LDS_BAR() do { asm volatile("s_waitcnt lgkmcnt(0)" ::: "memory"); __builtin_amdgcn_s_barrier(); asm volatile("" ::: "memory"); } while (0)
; DI void cv_issue_q(const CvJob& j, int idx, int lane, f32x4 (&v)[4], int r0) {
;     const float* W; int K, N, item; bf16* WT; const float* ks; cv_decode(j, idx, W, K, N, WT, ks, item);
;     const int nblk = N / 64, kb = item / nblk, nb = item % nblk, k0 = 64 * kb, n0 = 64 * nb, q = lane >> 4, c16 = lane & 15;
;     const char* ub = (const char*)(W + (size_t)(k0 + r0) * N + n0);
;     const unsigned vo = (unsigned)((16 * q) * N + 4 * c16) * 4u;
; #pragma unroll
;     for (int i = 0; i < 4; ++i) v[i] = *(const f32x4*)(ub + (size_t)i * N * 4 + vo);
; DI void rglru_scan_unit(Frame& F, const Mix0Args& a, int u) {
;     ...
;         { bf16x8 xf[4], waf[4], wxf[4]; unsigned xcr[4];
; #pragma unroll
;           for (int ks = 0; ks < 4; ++ks) { xf[ks] = *(const LAS bf16x8*)(XCc + (l0_ + fr) * S128 + ks * 64 + fq * 16);
;               waf[ks] = *(const LAS bf16x8*)(WAT + (16 * jtile + fr) * S128 + ks * 64 + fq * 16); wxf[ks] = *(const LAS bf16x8*)(WXT + (16 * jtile + fr) * S128 + ks * 64 + fq * 16); }
; #pragma unroll
;           for (int r = 0; r < 4; ++r) xcr[r] = *(const LAS unsigned short*)(XCc + (l0_ + 4 * fq + r) * S128 + (qq * 32 + jj) * 2);
;           f32x4 R = zero4, I = zero4;
; #pragma unroll
;           for (int ks = 0; ks < 4; ++ks) { R = __builtin_amdgcn_mfma_f32_16x16x32_bf16(xf[ks], waf[ks], R, 0, 0, 0); I = __builtin_amdgcn_mfma_f32_16x16x32_bf16(xf[ks], wxf[ks], I, 0, 0, 0); }
; #pragma unroll
;           for (int r = 0; r < 4; ++r) {
;               const float rr = fsigmoid(R[r] + bav), ig = fsigmoid(I[r] + bxv);
;               const float aa = fexp2(-sp8l2 * rr); const float om = __builtin_fmaf(-aa, aa, 1.0f);
;               av[r] = aa; uv[r] = __builtin_sqrtf(om) * (ig * bf2f(xcr[r]));
;               Hseg = aa * Hseg + uv[r]; Aseg *= aa; } }
;         const int sgi = ltile * 4 + fq;
;         SEGA[jj * 20 + sgi] = Aseg; SEGH[jj * 20 + sgi] = Hseg;
;         LDS_BAR();
.LBB0_277:
	s_lshr_b32 s79, s78, 6
	v_cvt_f32_u32_e32 v18, s79
	s_sub_i32 s90, 0, s79
	s_abs_i32 s89, s84
	s_ashr_i32 s88, s84, 31
	v_rcp_iflag_f32_e32 v18, v18
	v_mul_u32_u24_e32 v42, s78, v102
	v_or_b32_e32 v42, v42, v125
	v_lshlrev_b32_e32 v82, 2, v42
	v_mul_f32_e32 v18, 0x4f7ffffe, v18
	v_cvt_u32_f32_e32 v18, v18
	s_waitcnt vmcnt(26)
	v_lshlrev_b32_e32 v37, 16, v37
	s_waitcnt vmcnt(24)
	v_lshlrev_b32_e32 v34, 16, v34
	ds_read_b128 v[22:25], v103 offset:36864
	v_readfirstlane_b32 s91, v18
	s_mul_i32 s90, s90, s91
	s_mul_hi_u32 s90, s91, s90
	s_add_i32 s91, s91, s90
	s_mul_hi_u32 s90, s89, s91
	s_mul_i32 s91, s90, s79
	s_sub_i32 s89, s89, s91
	s_add_i32 vcc_lo, s90, 1
	s_sub_i32 s91, s89, s79
	s_cmp_ge_u32 s89, s79
	s_cselect_b32 s90, vcc_lo, s90
	s_cselect_b32 s89, s91, s89
	s_add_i32 s91, s90, 1
	s_cmp_ge_u32 s89, s79
	ds_read_b128 v[18:21], v164 offset:18432
	s_cselect_b32 s89, s91, s90
	s_xor_b32 s89, s89, s88
	s_sub_i32 s88, s89, s88
	s_mul_i32 s79, s88, s79
	s_lshl_b32 s88, s88, 6
	s_sub_i32 s79, s84, s79
	s_or_b32 s84, s88, 4
	s_mul_hi_i32 s91, s84, s78
	s_mul_i32 s90, s84, s78
	s_lshl_b32 s88, s79, 6
	s_lshl_b64 s[90:91], s[90:91], 2
	s_add_u32 s79, s40, s90
	ds_read_b128 v[26:29], v103 offset:46080
	ds_read_b128 v[30:33], v164 offset:18496
	ds_read_b128 v[38:41], v103 offset:36928
	ds_read_b128 v[42:45], v103 offset:46144
	ds_read_b128 v[46:49], v164 offset:18560
	s_addc_u32 s84, s41, s91
	s_ashr_i32 s89, s88, 31
	s_waitcnt lgkmcnt(5)
	v_mfma_f32_16x16x32_bf16 v[22:25], v[18:21], v[22:25], 0
	s_lshl_b64 s[40:41], s[88:89], 2
	s_add_u32 s40, s79, s40
	s_addc_u32 s41, s84, s41
	s_waitcnt lgkmcnt(4)
	v_mfma_f32_16x16x32_bf16 v[26:29], v[18:21], v[26:29], 0
	global_load_dwordx4 v[18:21], v82, s[40:41] nt
	s_lshl_b32 s96, s78, 2
	v_lshl_add_u64 v[64:65], s[40:41], 0, v[82:83]
	s_waitcnt lgkmcnt(2)
	v_mfma_f32_16x16x32_bf16 v[22:25], v[30:33], v[38:41], v[22:25]
	ds_read_b128 v[38:41], v103 offset:36992
	ds_read_b128 v[60:63], v164 offset:18624
	s_waitcnt lgkmcnt(3)
	v_mfma_f32_16x16x32_bf16 v[30:33], v[30:33], v[42:45], v[26:29]
	ds_read_b128 v[42:45], v103 offset:37056
	s_waitcnt lgkmcnt(2)
	v_mfma_f32_16x16x32_bf16 v[38:41], v[46:49], v[38:41], v[22:25]
	v_lshl_add_u64 v[26:27], v[64:65], 0, s[96:97]
	v_lshl_add_u64 v[64:65], v[26:27], 0, s[96:97]
	s_nop 0
	global_load_dwordx4 v[22:25], v[26:27], off nt
	s_nop 0
	global_load_dwordx4 v[26:29], v[64:65], off nt
	s_waitcnt lgkmcnt(0)
	v_mfma_f32_16x16x32_bf16 v[38:41], v[60:63], v[42:45], v[38:41]
	ds_read_b128 v[68:71], v103 offset:46208
	ds_read_b128 v[42:45], v103 offset:46272
	v_lshl_add_u64 v[64:65], v[64:65], 0, s[96:97]
	s_waitcnt lgkmcnt(1)
	v_mfma_f32_16x16x32_bf16 v[46:49], v[46:49], v[68:71], v[30:33]
	s_nop 2
	v_add_f32_e32 v38, v165, v38
	v_mul_f32_e32 v38, 0xbfb8aa3b, v38
	v_exp_f32_e32 v38, v38
	s_waitcnt lgkmcnt(0)
	v_mfma_f32_16x16x32_bf16 v[42:45], v[60:63], v[42:45], v[46:49]
	v_add_f32_e32 v39, v165, v39
	v_mul_f32_e32 v39, 0xbfb8aa3b, v39
	v_add_f32_e32 v30, 1.0, v38
	v_rcp_f32_e32 v38, v30
	v_exp_f32_e32 v39, v39
	global_load_dwordx4 v[30:33], v[64:65], off nt
	ds_read_u16 v47, v177 offset:18432
	ds_read_u16 v49, v177 offset:18720
	ds_read_u16 v59, v177 offset:19008
	ds_read_u16 v60, v177 offset:19296
	v_mul_f32_e64 v38, v38, -v168
	v_exp_f32_e32 v48, v38
	v_add_f32_e32 v38, v167, v42
	v_mul_f32_e32 v38, 0xbfb8aa3b, v38
	v_exp_f32_e32 v38, v38
	v_fma_f32 v42, -v48, v48, 1.0
	s_nop 0
	s_nop 0
	v_add_f32_e32 v38, 1.0, v38
	v_rcp_f32_e32 v38, v38
	s_nop 0
	v_sqrt_f32_e32 v46, v42
	v_add_f32_e32 v39, 1.0, v39
	v_rcp_f32_e32 v39, v39
	v_add_f32_e32 v40, v165, v40
	v_add_u32_e32 v61, -1, v46
	v_fma_f32 v62, -v61, v46, v42
	v_cmp_ge_f32_e64 s[40:41], 0, v62
	v_add_u32_e32 v62, 1, v46
	v_mul_f32_e32 v40, 0xbfb8aa3b, v40
	v_cndmask_b32_e64 v61, v46, v61, s[40:41]
	v_fma_f32 v46, -v62, v46, v42
	v_cmp_lt_f32_e64 s[40:41], 0, v46
	v_exp_f32_e32 v40, v40
	v_add_f32_e32 v41, v165, v41
	v_cndmask_b32_e64 v46, v61, v62, s[40:41]
	s_nop 0
	s_nop 0
	s_nop 0
	v_add_f32_e32 v40, 1.0, v40
	v_rcp_f32_e32 v40, v40
	v_mov_b32_e32 v42, v46
	s_waitcnt lgkmcnt(3)
	v_lshlrev_b32_e32 v46, 16, v47
	v_mul_f32_e32 v38, v38, v46
	v_mul_f32_e32 v64, v38, v42
	v_mul_f32_e64 v38, v39, -v168
	v_exp_f32_e32 v39, v38
	v_add_f32_e32 v38, v167, v43
	v_mul_f32_e32 v38, 0xbfb8aa3b, v38
	v_exp_f32_e32 v38, v38
	v_fma_f32 v42, -v39, v39, 1.0
	s_nop 0
	s_nop 0
	v_add_f32_e32 v38, 1.0, v38
	v_rcp_f32_e32 v38, v38
	s_nop 0
	v_sqrt_f32_e32 v43, v42
	v_mul_f32_e64 v40, v40, -v168
	v_exp_f32_e32 v65, v40
	v_add_f32_e32 v40, v167, v44
	v_add_u32_e32 v47, -1, v43
	v_fma_f32 v61, -v47, v43, v42
	v_cmp_ge_f32_e64 s[40:41], 0, v61
	v_add_u32_e32 v61, 1, v43
	v_fma_f32 v46, 0, v48, v64
	v_cndmask_b32_e64 v47, v43, v47, s[40:41]
	v_fma_f32 v43, -v61, v43, v42
	v_cmp_lt_f32_e64 s[40:41], 0, v43
	v_mul_f32_e32 v40, 0xbfb8aa3b, v40
	v_exp_f32_e32 v40, v40
	v_cndmask_b32_e64 v43, v47, v61, s[40:41]
	s_nop 0
	s_nop 0
	s_nop 0
	v_mul_f32_e32 v41, 0xbfb8aa3b, v41
	v_exp_f32_e32 v41, v41
	v_mov_b32_e32 v42, v43
	s_waitcnt lgkmcnt(2)
	v_lshlrev_b32_e32 v43, 16, v49
	v_mul_f32_e32 v38, v38, v43
	v_mul_f32_e32 v49, v38, v42
	v_fma_f32 v42, -v65, v65, 1.0
	s_nop 0
	s_nop 0
	v_fma_f32 v38, v39, v46, v49
	v_add_f32_e32 v40, 1.0, v40
	s_nop 0
	v_sqrt_f32_e32 v43, v42
	v_rcp_f32_e32 v40, v40
	v_add_f32_e32 v41, 1.0, v41
	v_rcp_f32_e32 v41, v41
	v_add_u32_e32 v46, -1, v43
	v_fma_f32 v47, -v46, v43, v42
	v_cmp_ge_f32_e64 s[40:41], 0, v47
	v_add_u32_e32 v47, 1, v43
	v_mul_f32_e32 v44, v48, v39
	v_cndmask_b32_e64 v46, v43, v46, s[40:41]
	v_fma_f32 v43, -v47, v43, v42
	v_cmp_lt_f32_e64 s[40:41], 0, v43
	s_nop 1
	v_cndmask_b32_e64 v43, v46, v47, s[40:41]
	s_nop 0
	s_nop 0
	s_nop 0
	s_nop 1
	v_mov_b32_e32 v42, v43
	s_waitcnt lgkmcnt(1)
	v_lshlrev_b32_e32 v43, 16, v59
	v_mul_f32_e32 v40, v40, v43
	v_mul_f32_e32 v59, v40, v42
	v_fma_f32 v40, v65, v38, v59
	v_mul_f32_e64 v38, v41, -v168
	v_exp_f32_e32 v80, v38
	v_add_f32_e32 v38, v167, v45
	v_mul_f32_e32 v38, 0xbfb8aa3b, v38
	v_exp_f32_e32 v38, v38
	v_fma_f32 v41, -v80, v80, 1.0
	s_nop 0
	s_nop 0
	v_mul_f32_e32 v43, v65, v44
	v_add_f32_e32 v38, 1.0, v38
	s_nop 0
	v_sqrt_f32_e32 v42, v41
	v_rcp_f32_e32 v38, v38
	v_add_u32_e32 v44, -1, v42
	v_fma_f32 v45, -v44, v42, v41
	v_cmp_ge_f32_e64 s[40:41], 0, v45
	v_add_u32_e32 v45, 1, v42
	s_nop 0
	v_cndmask_b32_e64 v44, v42, v44, s[40:41]
	v_fma_f32 v42, -v45, v42, v41
	v_cmp_lt_f32_e64 s[40:41], 0, v42
	s_nop 1
	v_cndmask_b32_e64 v42, v44, v45, s[40:41]
	s_nop 0
	s_nop 0
	s_nop 0
	s_mov_b32 s40, 0x25600000
	s_nop 0
	v_mov_b32_e32 v41, v42
	s_waitcnt lgkmcnt(0)
	v_lshlrev_b32_e32 v42, 16, v60
	v_mul_f32_e32 v38, v38, v42
	v_mul_f32_e32 v38, v38, v41
	v_fma_f32 v40, v80, v40, v38
	v_mul_f32_e32 v41, v80, v43
	ds_write2st64_b32 v150, v41, v40 offset0:236 offset1:246
	s_waitcnt lgkmcnt(0)
	s_barrier
; #define LAS __attribute__((address_space(3)))
; DI float bf2f(unsigned h) { return __uint_as_float(h << 16); }
; DI unsigned pk2(float lo, float hi) { f32x2 v = {lo, hi}; bf16v2 b = __builtin_convertvector(v, bf16v2); return __builtin_bit_cast(unsigned, b); }
; DI float fsilu(float x) { return x * fsigmoid(x); }
; DI void rglru_scan_unit(Frame& F, const Mix0Args& a, int u) {
;     ...
;         float carry = HPREV[jj * 20 + (n & 1)]; float sa[15], sh[15];
;         { f32x4 a4[4], h4[4];
; #pragma unroll
;           for (int i = 0; i < 4; ++i) { a4[i] = *(const LAS f32x4*)(SEGA + jj * 20 + 4 * i); h4[i] = *(const LAS f32x4*)(SEGH + jj * 20 + 4 * i); }
; #pragma unroll
;           for (int s = 0; s < 15; ++s) { sa[s] = a4[s >> 2][s & 3]; sh[s] = h4[s >> 2][s & 3]; } }
; #pragma unroll
;         for (int s = 0; s < 15; ++s) carry = (s < sgi) ? sa[s] * carry + sh[s] : carry;
; #pragma unroll
;         for (int r = 0; r < 4; ++r) { carry = av[r] * carry + uv[r];
;             const float o = carry * fsilu(bf2f(gb_cur[r]));
;             obcol[(row0 + l0_ + 4 * fq + r) * a.out_ld] = (bf16)(pk2(o, 0.f) & 0xffffu); }
;         if (sgi == 15) HPREV[jj * 20 + ((n + 1) & 1)] = carry;
	ds_read_b32 v81, v149 offset:55364
	ds_read_b128 v[40:43], v149 offset:60416
	ds_read_b128 v[44:47], v149 offset:62976
	ds_read_b128 v[60:63], v149 offset:60432
	ds_read_b128 v[68:71], v149 offset:60448
	ds_read_b128 v[72:75], v149 offset:62992
	ds_read_b128 v[76:79], v149 offset:63008
	ds_read_b128 v[178:181], v149 offset:60464
	ds_read_b128 v[184:187], v149 offset:63024
	s_waitcnt lgkmcnt(6)
	v_fma_f32 v40, v81, v40, v44
	v_cndmask_b32_e64 v40, v40, v81, s[10:11]
	v_fma_f32 v41, v41, v40, v45
	v_cndmask_b32_e64 v40, v40, v41, s[12:13]
	v_fma_f32 v41, v42, v40, v46
	v_cndmask_b32_e64 v40, v40, v41, s[14:15]
	v_fmac_f32_e32 v47, v43, v40
	v_cndmask_b32_e64 v40, v47, v40, s[0:1]
	s_waitcnt lgkmcnt(3)
	v_fma_f32 v41, v60, v40, v72
	v_cndmask_b32_e64 v40, v40, v41, s[16:17]
	v_fma_f32 v41, v61, v40, v73
	v_cndmask_b32_e64 v40, v40, v41, s[18:19]
	v_fma_f32 v41, v62, v40, v74
	v_cndmask_b32_e64 v40, v40, v41, s[20:21]
	v_fmac_f32_e32 v75, v63, v40
	v_cndmask_b32_e64 v40, v40, v75, s[38:39]
	s_waitcnt lgkmcnt(2)
	v_fma_f32 v41, v68, v40, v76
	v_cndmask_b32_e64 v40, v40, v41, s[22:23]
	v_fma_f32 v41, v69, v40, v77
	v_cndmask_b32_e64 v40, v40, v41, s[24:25]
	v_fma_f32 v41, v70, v40, v78
	v_cndmask_b32_e64 v40, v40, v41, s[26:27]
	v_fmac_f32_e32 v79, v71, v40
	v_mul_f32_e32 v42, 0xbfb8aa3b, v37
	v_cndmask_b32_e64 v40, v40, v79, s[4:5]
	v_exp_f32_e32 v42, v42
	s_waitcnt lgkmcnt(0)
	v_fma_f32 v41, v178, v40, v184
	v_cndmask_b32_e64 v40, v40, v41, s[28:29]
	v_fma_f32 v41, v179, v40, v185
	v_cndmask_b32_e64 v40, v40, v41, s[30:31]
	v_add_f32_e32 v41, 1.0, v42
	v_rcp_f32_e32 v41, v41
	v_fmac_f32_e32 v186, v180, v40
	v_cndmask_b32_e64 v40, v40, v186, s[34:35]
	v_fmac_f32_e32 v64, v48, v40
	v_mul_f32_e32 v37, v41, v37
	v_lshlrev_b32_e32 v41, 16, v36
	v_mul_f32_e32 v36, 0xbfb8aa3b, v41
	v_exp_f32_e32 v42, v36
	v_mul_f32_e32 v37, v37, v64
	v_add_co_u32_e32 v36, vcc, s40, v66
	v_cvt_pk_bf16_f32 v40, v37, s0
	s_nop 0
	v_addc_co_u32_e32 v37, vcc, 0, v67, vcc
	global_store_short v[36:37], v40, off
	v_add_f32_e32 v36, 1.0, v42
	v_rcp_f32_e32 v36, v36
	v_mul_f32_e32 v37, 0xbfb8aa3b, v34
	v_exp_f32_e32 v37, v37
	v_fmac_f32_e32 v49, v39, v64
	v_mul_f32_e32 v36, v36, v41
	v_mul_f32_e32 v36, v36, v49
	v_cvt_pk_bf16_f32 v39, v36, s0
	v_add_f32_e32 v36, 1.0, v37
	s_mov_b32 s40, 0x2560c000
	v_rcp_f32_e32 v40, v36
	v_add_co_u32_e32 v36, vcc, s40, v66
	v_fmac_f32_e32 v59, v65, v49
	s_nop 0
	v_addc_co_u32_e32 v37, vcc, 0, v67, vcc
	global_store_short v[36:37], v39, off
	s_waitcnt vmcnt(29)
	v_lshlrev_b32_e32 v36, 16, v35
	v_mul_f32_e32 v35, 0xbfb8aa3b, v36
	v_exp_f32_e32 v35, v35
	v_mul_f32_e32 v34, v40, v34
	v_mul_f32_e32 v34, v34, v59
	s_mov_b32 s40, 0x25618000
	v_add_f32_e32 v35, 1.0, v35
	v_rcp_f32_e32 v39, v35
	v_cvt_pk_bf16_f32 v37, v34, s0
	v_add_co_u32_e32 v34, vcc, s40, v66
	v_fmac_f32_e32 v38, v80, v59
	s_nop 0
	v_addc_co_u32_e32 v35, vcc, 0, v67, vcc
	global_store_short v[34:35], v37, off
	v_mul_f32_e32 v34, v39, v36
	v_mul_f32_e32 v34, v34, v38
	v_cvt_pk_bf16_f32 v36, v34, s0
	s_mov_b64 s[100:101], 0x25624000
	v_lshl_add_u64 v[34:35], v[66:67], 0, s[100:101]
	global_store_short v[34:35], v36, off
	s_and_saveexec_b64 s[40:41], s[34:35]
	ds_write_b32 v149, v38 offset:55360
	s_or_b64 exec, exec, s[40:41]
	s_waitcnt vmcnt(22)
	v_lshlrev_b32_e32 v34, 16, v130
	v_and_b32_e32 v35, 0xffff0000, v130
	v_pk_fma_f32 v[34:35], v[104:105], v[34:35], v[100:101]
	s_waitcnt vmcnt(21)
	v_lshlrev_b32_e32 v36, 16, v132
	v_and_b32_e32 v37, 0xffff0000, v132
	v_pk_fma_f32 v[34:35], v[106:107], v[36:37], v[34:35]
	s_waitcnt vmcnt(20)
	v_lshlrev_b32_e32 v38, 16, v134
	v_and_b32_e32 v39, 0xffff0000, v134
	v_pk_fma_f32 v[34:35], v[108:109], v[38:39], v[34:35]
	s_waitcnt vmcnt(19)
	v_lshlrev_b32_e32 v40, 16, v169
	v_and_b32_e32 v41, 0xffff0000, v169
	v_pk_fma_f32 v[34:35], v[110:111], v[40:41], v[34:35]
	s_or_b32 s40, s93, 2
	v_cvt_pk_bf16_f32 v42, v34, v35
	v_pk_fma_f32 v[34:35], v[104:105], v[36:37], v[100:101]
	s_waitcnt vmcnt(18)
	v_lshlrev_b32_e32 v36, 16, v170
	v_pk_fma_f32 v[34:35], v[106:107], v[38:39], v[34:35]
	v_and_b32_e32 v37, 0xffff0000, v170
	v_pk_fma_f32 v[34:35], v[108:109], v[40:41], v[34:35]
	s_cmpk_gt_u32 s40, 0x7d
	v_pk_fma_f32 v[34:35], v[110:111], v[36:37], v[34:35]
	s_nop 0
	v_cvt_pk_bf16_f32 v34, v34, v35
	ds_write2_b32 v183, v42, v34 offset1:72
	v_pk_fma_f32 v[34:35], v[104:105], v[38:39], v[100:101]
	s_waitcnt vmcnt(17)
	v_lshlrev_b32_e32 v38, 16, v171
	v_pk_fma_f32 v[34:35], v[106:107], v[40:41], v[34:35]
	v_and_b32_e32 v39, 0xffff0000, v171
	v_pk_fma_f32 v[34:35], v[108:109], v[36:37], v[34:35]
	s_nop 0
	v_pk_fma_f32 v[34:35], v[110:111], v[38:39], v[34:35]
	s_nop 0
	v_cvt_pk_bf16_f32 v42, v34, v35
	v_pk_fma_f32 v[34:35], v[104:105], v[40:41], v[100:101]
	s_waitcnt vmcnt(16)
	v_lshlrev_b32_e32 v40, 16, v172
	v_pk_fma_f32 v[34:35], v[106:107], v[36:37], v[34:35]
	v_and_b32_e32 v41, 0xffff0000, v172
	v_pk_fma_f32 v[34:35], v[108:109], v[38:39], v[34:35]
	s_nop 0
	v_pk_fma_f32 v[34:35], v[110:111], v[40:41], v[34:35]
	s_nop 0
	v_cvt_pk_bf16_f32 v34, v34, v35
	ds_write2_b32 v183, v42, v34 offset0:144 offset1:216
	v_pk_fma_f32 v[34:35], v[104:105], v[36:37], v[100:101]
	s_waitcnt vmcnt(15)
	v_lshlrev_b32_e32 v36, 16, v173
	v_pk_fma_f32 v[34:35], v[106:107], v[38:39], v[34:35]
	v_and_b32_e32 v37, 0xffff0000, v173
	v_pk_fma_f32 v[34:35], v[108:109], v[40:41], v[34:35]
	s_nop 0
	v_pk_fma_f32 v[34:35], v[110:111], v[36:37], v[34:35]
	s_nop 0
	v_cvt_pk_bf16_f32 v42, v34, v35
	v_pk_fma_f32 v[34:35], v[104:105], v[38:39], v[100:101]
	s_waitcnt vmcnt(14)
	v_lshlrev_b32_e32 v38, 16, v174
	v_pk_fma_f32 v[34:35], v[106:107], v[40:41], v[34:35]
	v_and_b32_e32 v39, 0xffff0000, v174
	v_pk_fma_f32 v[34:35], v[108:109], v[36:37], v[34:35]
	s_nop 0
	v_pk_fma_f32 v[34:35], v[110:111], v[38:39], v[34:35]
	s_nop 0
	v_cvt_pk_bf16_f32 v34, v34, v35
	ds_write2_b32 v182, v42, v34 offset0:32 offset1:104
	v_pk_fma_f32 v[34:35], v[104:105], v[40:41], v[100:101]
	s_waitcnt vmcnt(13)
	v_lshlrev_b32_e32 v40, 16, v175
	v_pk_fma_f32 v[34:35], v[106:107], v[36:37], v[34:35]
	v_and_b32_e32 v41, 0xffff0000, v175
	v_pk_fma_f32 v[34:35], v[108:109], v[38:39], v[34:35]
	s_nop 0
	v_pk_fma_f32 v[34:35], v[110:111], v[40:41], v[34:35]
	s_nop 0
	v_cvt_pk_bf16_f32 v42, v34, v35
	v_pk_fma_f32 v[34:35], v[104:105], v[36:37], v[100:101]
	s_waitcnt vmcnt(12)
	v_lshlrev_b32_e32 v36, 16, v176
	v_pk_fma_f32 v[34:35], v[106:107], v[38:39], v[34:35]
	v_and_b32_e32 v37, 0xffff0000, v176
	v_pk_fma_f32 v[34:35], v[108:109], v[40:41], v[34:35]
	s_nop 0
	v_pk_fma_f32 v[34:35], v[110:111], v[36:37], v[34:35]
	s_nop 0
	v_cvt_pk_bf16_f32 v34, v34, v35
	ds_write2_b32 v182, v42, v34 offset0:176 offset1:248
	s_cbranch_scc1 .LBB0_281
	s_mov_b64 s[100:101], 0x25ee4000
	v_lshl_add_u64 v[34:35], v[50:51], 0, s[100:101]
	global_load_dword v130, v[34:35], off
	s_mov_b64 s[100:101], 0x25ef0000
	v_lshl_add_u64 v[34:35], v[50:51], 0, s[100:101]
	global_load_dword v132, v[34:35], off
	s_mov_b64 s[100:101], 0x25efc000
	v_lshl_add_u64 v[34:35], v[50:51], 0, s[100:101]
	global_load_dword v134, v[34:35], off
	s_mov_b64 s[100:101], 0x25f08000
	v_lshl_add_u64 v[34:35], v[50:51], 0, s[100:101]
	global_load_dword v169, v[34:35], off
	s_mov_b64 s[100:101], 0x25f14000
	v_lshl_add_u64 v[34:35], v[50:51], 0, s[100:101]
	global_load_dword v170, v[34:35], off
	s_mov_b64 s[100:101], 0x25f20000
	v_lshl_add_u64 v[34:35], v[50:51], 0, s[100:101]
	global_load_dword v171, v[34:35], off
	s_mov_b64 s[100:101], 0x25f2c000
	v_lshl_add_u64 v[34:35], v[50:51], 0, s[100:101]
	global_load_dword v172, v[34:35], off
	s_mov_b64 s[100:101], 0x25f38000
	v_lshl_add_u64 v[34:35], v[50:51], 0, s[100:101]
	global_load_dword v173, v[34:35], off
	s_mov_b64 s[100:101], 0x25f44000
	v_lshl_add_u64 v[34:35], v[50:51], 0, s[100:101]
	global_load_dword v174, v[34:35], off
	s_mov_b64 s[100:101], 0x25f50000
	v_lshl_add_u64 v[34:35], v[50:51], 0, s[100:101]
	global_load_dword v175, v[34:35], off
	s_mov_b64 s[100:101], 0x25f5c000
	v_lshl_add_u64 v[34:35], v[50:51], 0, s[100:101]
	global_load_dword v176, v[34:35], off

; #define LAS __attribute__((address_space(3)))
; DI float bf2f(unsigned h) { return __uint_as_float(h << 16); }
; DI float fexp2(float x) { return __builtin_amdgcn_exp2f(x); }
; DI float fsigmoid(float x) { return frcp(1.0f + fexp2(-LOG2E * x)); }
; #define LDS_BAR() do { asm volatile("s_waitcnt lgkmcnt(0)" ::: "memory"); __builtin_amdgcn_s_barrier(); asm volatile("" ::: "memory"); } while (0)
; DI void cv_issue_q(const CvJob& j, int idx, int lane, f32x4 (&v)[4], int r0) {
;     const float* W; int K, N, item; bf16* WT; const float* ks; cv_decode(j, idx, W, K, N, WT, ks, item);
;     const int nblk = N / 64, kb = item / nblk, nb = item % nblk, k0 = 64 * kb, n0 = 64 * nb, q = lane >> 4, c16 = lane & 15;
;     const char* ub = (const char*)(W + (size_t)(k0 + r0) * N + n0);
;     const unsigned vo = (unsigned)((16 * q) * N + 4 * c16) * 4u;
; #pragma unroll
;     for (int i = 0; i < 4; ++i) v[i] = *(const f32x4*)(ub + (size_t)i * N * 4 + vo);
; DI void rglru_scan_unit(Frame& F, const Mix0Args& a, int u) {
;     ...
;         { bf16x8 xf[4], waf[4], wxf[4]; unsigned xcr[4];
; #pragma unroll
;           for (int ks = 0; ks < 4; ++ks) { xf[ks] = *(const LAS bf16x8*)(XCc + (l0_ + fr) * S128 + ks * 64 + fq * 16);
;               waf[ks] = *(const LAS bf16x8*)(WAT + (16 * jtile + fr) * S128 + ks * 64 + fq * 16); wxf[ks] = *(const LAS bf16x8*)(WXT + (16 * jtile + fr) * S128 + ks * 64 + fq * 16); }
; #pragma unroll
;           for (int r = 0; r < 4; ++r) xcr[r] = *(const LAS unsigned short*)(XCc + (l0_ + 4 * fq + r) * S128 + (qq * 32 + jj) * 2);
;           f32x4 R = zero4, I = zero4;
; #pragma unroll
;           for (int ks = 0; ks < 4; ++ks) { R = __builtin_amdgcn_mfma_f32_16x16x32_bf16(xf[ks], waf[ks], R, 0, 0, 0); I = __builtin_amdgcn_mfma_f32_16x16x32_bf16(xf[ks], wxf[ks], I, 0, 0, 0); }
; #pragma unroll
;           for (int r = 0; r < 4; ++r) {
;               const float rr = fsigmoid(R[r] + bav), ig = fsigmoid(I[r] + bxv);
;               const float aa = fexp2(-sp8l2 * rr); const float om = __builtin_fmaf(-aa, aa, 1.0f);
;               av[r] = aa; uv[r] = __builtin_sqrtf(om) * (ig * bf2f(xcr[r]));
;               Hseg = aa * Hseg + uv[r]; Aseg *= aa; } }
;         const int sgi = ltile * 4 + fq;
;         SEGA[jj * 20 + sgi] = Aseg; SEGH[jj * 20 + sgi] = Hseg;
;         LDS_BAR();
.LBB0_287:
	s_lshr_b32 s79, s78, 6
	v_cvt_f32_u32_e32 v34, s79
	s_sub_i32 s90, 0, s79
	s_abs_i32 s89, s84
	s_ashr_i32 s88, s84, 31
	v_rcp_iflag_f32_e32 v34, v34
	v_mul_u32_u24_e32 v63, s78, v102
	v_or_b32_e32 v63, v63, v125
	v_lshlrev_b32_e32 v82, 2, v63
	v_mul_f32_e32 v34, 0x4f7ffffe, v34
	v_cvt_u32_f32_e32 v34, v34
	s_waitcnt vmcnt(15)
	v_lshlrev_b32_e32 v58, 16, v58
	s_waitcnt vmcnt(14)
	v_lshlrev_b32_e32 v56, 16, v56
	s_waitcnt vmcnt(13)
	v_lshlrev_b32_e32 v55, 16, v55
	v_readfirstlane_b32 s91, v34
	ds_read_b128 v[34:37], v164
	ds_read_b128 v[38:41], v103 offset:36864
	s_mul_i32 s90, s90, s91
	s_mul_hi_u32 s90, s91, s90
	s_add_i32 s91, s91, s90
	s_mul_hi_u32 s90, s89, s91
	s_mul_i32 s91, s90, s79
	s_sub_i32 s89, s89, s91
	s_add_i32 vcc_lo, s90, 1
	s_sub_i32 s91, s89, s79
	s_cmp_ge_u32 s89, s79
	ds_read_b128 v[42:45], v103 offset:46080
	ds_read_b128 v[46:49], v164 offset:64
	ds_read_b128 v[68:71], v103 offset:36928
	ds_read_b128 v[72:75], v103 offset:46144
	ds_read_b128 v[76:79], v164 offset:128
	s_cselect_b32 s90, vcc_lo, s90
	s_waitcnt lgkmcnt(5)
	v_mfma_f32_16x16x32_bf16 v[38:41], v[34:37], v[38:41], 0
	s_cselect_b32 s89, s91, s89
	s_add_i32 s91, s90, 1
	s_cmp_ge_u32 s89, s79
	s_cselect_b32 s89, s91, s90
	s_waitcnt lgkmcnt(4)
	v_mfma_f32_16x16x32_bf16 v[34:37], v[34:37], v[42:45], 0
	s_xor_b32 s89, s89, s88
	s_sub_i32 s88, s89, s88
	s_mul_i32 s79, s88, s79
	s_waitcnt lgkmcnt(2)
	v_mfma_f32_16x16x32_bf16 v[38:41], v[46:49], v[68:71], v[38:41]
	ds_read_b128 v[42:45], v103 offset:36992
	ds_read_b128 v[68:71], v164 offset:192
	s_lshl_b32 s88, s88, 6
	s_sub_i32 s79, s84, s79
	s_or_b32 s84, s88, 8
	s_waitcnt lgkmcnt(3)
	v_mfma_f32_16x16x32_bf16 v[34:37], v[46:49], v[72:75], v[34:37]
	ds_read_b128 v[46:49], v103 offset:37056
	s_mul_hi_i32 s91, s84, s78
	s_mul_i32 s90, s84, s78
	s_waitcnt lgkmcnt(2)
	v_mfma_f32_16x16x32_bf16 v[72:75], v[76:79], v[42:45], v[38:41]
	s_lshl_b32 s88, s79, 6
	s_lshl_b64 s[90:91], s[90:91], 2
	s_add_u32 s79, s40, s90
	s_addc_u32 s84, s41, s91
	s_ashr_i32 s89, s88, 31
	s_lshl_b64 s[40:41], s[88:89], 2
	s_waitcnt lgkmcnt(0)
	v_mfma_f32_16x16x32_bf16 v[72:75], v[68:71], v[46:49], v[72:75]
	s_add_u32 s40, s79, s40
	s_addc_u32 s41, s84, s41
	s_lshl_b32 s96, s78, 2
	v_lshl_add_u64 v[64:65], s[40:41], 0, v[82:83]
	v_lshl_add_u64 v[64:65], v[64:65], 0, s[96:97]
	s_nop 2
	v_add_f32_e32 v46, v165, v72
	v_lshl_add_u64 v[80:81], v[64:65], 0, s[96:97]
	global_load_dwordx4 v[38:41], v[64:65], off nt
	global_load_dwordx4 v[42:45], v[80:81], off nt
	ds_read_b128 v[178:181], v103 offset:46208
	ds_read_b128 v[182:185], v103 offset:46272
	v_mul_f32_e32 v46, 0xbfb8aa3b, v46
	v_exp_f32_e32 v48, v46
	s_waitcnt lgkmcnt(1)
	v_mfma_f32_16x16x32_bf16 v[76:79], v[76:79], v[178:181], v[34:37]
	v_lshl_add_u64 v[46:47], v[80:81], 0, s[96:97]
	v_add_f32_e32 v73, v165, v73
	s_nop 0
	v_add_f32_e32 v34, 1.0, v48
	v_rcp_f32_e32 v63, v34
	s_waitcnt lgkmcnt(0)
	v_mfma_f32_16x16x32_bf16 v[68:71], v[68:71], v[182:185], v[76:79]
	global_load_dwordx4 v[34:37], v82, s[40:41] nt
	s_nop 0
	global_load_dwordx4 v[46:49], v[46:47], off nt
	v_mul_f32_e32 v73, 0xbfb8aa3b, v73
	v_mul_f32_e64 v63, v63, -v168
	v_exp_f32_e32 v64, v63
	s_nop 1
	v_add_f32_e32 v63, v167, v68
	v_mul_f32_e32 v63, 0xbfb8aa3b, v63
	v_exp_f32_e32 v63, v63
	v_fma_f32 v65, -v64, v64, 1.0
	s_nop 0
	s_nop 0
	v_exp_f32_e32 v73, v73
	v_add_f32_e32 v63, 1.0, v63
	s_nop 0
	v_sqrt_f32_e32 v68, v65
	v_rcp_f32_e32 v63, v63
	ds_read_u16 v72, v113
	ds_read_u16 v76, v113 offset:288
	ds_read_u16 v77, v113 offset:576
	ds_read_u16 v78, v113 offset:864
	v_add_u32_e32 v79, -1, v68
	v_fma_f32 v80, -v79, v68, v65
	v_cmp_ge_f32_e64 s[40:41], 0, v80
	v_add_u32_e32 v80, 1, v68
	s_waitcnt lgkmcnt(3)
	v_lshlrev_b32_e32 v72, 16, v72
	v_cndmask_b32_e64 v79, v68, v79, s[40:41]
	v_fma_f32 v68, -v80, v68, v65
	v_cmp_lt_f32_e64 s[40:41], 0, v68
	v_mul_f32_e32 v63, v63, v72
	s_nop 0
	v_cndmask_b32_e64 v68, v79, v80, s[40:41]
	s_nop 0
	s_nop 0
	s_nop 0
	s_nop 1
	v_mov_b32_e32 v65, v68
	v_add_f32_e32 v68, 1.0, v73
	v_rcp_f32_e32 v68, v68
	v_mul_f32_e32 v80, v63, v65
	v_mul_f32_e64 v63, v68, -v168
	v_exp_f32_e32 v81, v63
	v_add_f32_e32 v63, v167, v69
	v_mul_f32_e32 v63, 0xbfb8aa3b, v63
	v_exp_f32_e32 v63, v63
	v_fma_f32 v65, -v81, v81, 1.0
	s_nop 0
	s_nop 0
	v_add_f32_e32 v63, 1.0, v63
	v_rcp_f32_e32 v63, v63
	s_nop 0
	v_sqrt_f32_e32 v68, v65
	v_fma_f32 v69, 0, v64, v80
	v_add_u32_e32 v72, -1, v68
	v_fma_f32 v73, -v72, v68, v65
	v_cmp_ge_f32_e64 s[40:41], 0, v73
	v_add_u32_e32 v73, 1, v68
	s_nop 0
	v_cndmask_b32_e64 v72, v68, v72, s[40:41]
	v_fma_f32 v68, -v73, v68, v65
	v_cmp_lt_f32_e64 s[40:41], 0, v68
	s_nop 1
	v_cndmask_b32_e64 v68, v72, v73, s[40:41]
	s_nop 0
	s_nop 0
	v_add_f32_e32 v72, v165, v74
	v_mul_f32_e32 v72, 0xbfb8aa3b, v72
	v_exp_f32_e32 v72, v72
	s_nop 0
	v_add_f32_e32 v72, 1.0, v72
	v_rcp_f32_e32 v72, v72
	v_mov_b32_e32 v65, v68
	s_waitcnt lgkmcnt(2)
	v_lshlrev_b32_e32 v68, 16, v76
	v_mul_f32_e32 v63, v63, v68
	v_mul_f32_e32 v82, v63, v65
	v_mul_f32_e64 v65, v72, -v168
	v_exp_f32_e32 v122, v65
	v_fma_f32 v63, v81, v69, v82
	v_add_f32_e32 v65, v167, v70
	v_mul_f32_e32 v65, 0xbfb8aa3b, v65
	v_fma_f32 v68, -v122, v122, 1.0
	s_nop 0
	s_nop 0
	v_exp_f32_e32 v65, v65
	v_mul_f32_e32 v70, v64, v81
	s_nop 0
	v_sqrt_f32_e32 v69, v68
	v_add_f32_e32 v65, 1.0, v65
	v_rcp_f32_e32 v65, v65
	v_mul_f32_e32 v70, v122, v70
	v_add_u32_e32 v72, -1, v69
	v_fma_f32 v73, -v72, v69, v68
	v_cmp_ge_f32_e64 s[40:41], 0, v73
	v_add_u32_e32 v73, 1, v69
	s_nop 0
	v_cndmask_b32_e64 v72, v69, v72, s[40:41]
	v_fma_f32 v69, -v73, v69, v68
	v_cmp_lt_f32_e64 s[40:41], 0, v69
	s_nop 1
	v_cndmask_b32_e64 v69, v72, v73, s[40:41]
	s_nop 0
	s_nop 0
	v_add_f32_e32 v72, v165, v75
	v_mul_f32_e32 v72, 0xbfb8aa3b, v72
	v_exp_f32_e32 v72, v72
	s_nop 0
	v_add_f32_e32 v72, 1.0, v72
	v_rcp_f32_e32 v72, v72
	v_mov_b32_e32 v68, v69
	s_waitcnt lgkmcnt(1)
	v_lshlrev_b32_e32 v69, 16, v77
	v_mul_f32_e32 v65, v65, v69
	v_mul_f32_e32 v124, v65, v68
	v_fma_f32 v65, v122, v63, v124
	v_mul_f32_e64 v63, v72, -v168
	v_exp_f32_e32 v126, v63
	v_add_f32_e32 v63, v167, v71
	v_mul_f32_e32 v63, 0xbfb8aa3b, v63
	v_exp_f32_e32 v63, v63
	v_fma_f32 v68, -v126, v126, 1.0
	s_nop 0
	s_nop 0
	v_add_f32_e32 v63, 1.0, v63
	v_rcp_f32_e32 v63, v63
	s_nop 0
	v_sqrt_f32_e32 v69, v68
	s_nop 0
	v_add_u32_e32 v71, -1, v69
	v_fma_f32 v72, -v71, v69, v68
	v_cmp_ge_f32_e64 s[40:41], 0, v72
	v_add_u32_e32 v72, 1, v69
	s_nop 0
	v_cndmask_b32_e64 v71, v69, v71, s[40:41]
	v_fma_f32 v69, -v72, v69, v68
	v_cmp_lt_f32_e64 s[40:41], 0, v69
	s_nop 1
	v_cndmask_b32_e64 v69, v71, v72, s[40:41]
	s_nop 0
	s_nop 0
	s_nop 0
	s_mov_b32 s40, 0x25900000
	s_nop 0
	v_mov_b32_e32 v68, v69
	s_waitcnt lgkmcnt(0)
	v_lshlrev_b32_e32 v69, 16, v78
	v_mul_f32_e32 v63, v63, v69
	v_mul_f32_e32 v63, v63, v68
	v_fma_f32 v65, v126, v65, v63
	v_mul_f32_e32 v68, v126, v70
	ds_write2st64_b32 v150, v68, v65 offset0:216 offset1:226
	s_waitcnt lgkmcnt(0)
	s_barrier
; #define LAS __attribute__((address_space(3)))
; DI float bf2f(unsigned h) { return __uint_as_float(h << 16); }
; DI unsigned pk2(float lo, float hi) { f32x2 v = {lo, hi}; bf16v2 b = __builtin_convertvector(v, bf16v2); return __builtin_bit_cast(unsigned, b); }
; DI float fsilu(float x) { return x * fsigmoid(x); }
; DI void rglru_scan_unit(Frame& F, const Mix0Args& a, int u) {
;     ...
;         float carry = HPREV[jj * 20 + (n & 1)]; float sa[15], sh[15];
;         { f32x4 a4[4], h4[4];
; #pragma unroll
;           for (int i = 0; i < 4; ++i) { a4[i] = *(const LAS f32x4*)(SEGA + jj * 20 + 4 * i); h4[i] = *(const LAS f32x4*)(SEGH + jj * 20 + 4 * i); }
; #pragma unroll
;           for (int s = 0; s < 15; ++s) { sa[s] = a4[s >> 2][s & 3]; sh[s] = h4[s >> 2][s & 3]; } }
; #pragma unroll
;         for (int s = 0; s < 15; ++s) carry = (s < sgi) ? sa[s] * carry + sh[s] : carry;
; #pragma unroll
;         for (int r = 0; r < 4; ++r) { carry = av[r] * carry + uv[r];
;             const float o = carry * fsilu(bf2f(gb_cur[r]));
;             obcol[(row0 + l0_ + 4 * fq + r) * a.out_ld] = (bf16)(pk2(o, 0.f) & 0xffffu); }
;         if (sgi == 15) HPREV[jj * 20 + ((n + 1) & 1)] = carry;
	ds_read_b32 v65, v149 offset:55360
	ds_read_b128 v[68:71], v149 offset:57856
	ds_read_b128 v[72:75], v149 offset:57872
	ds_read_b128 v[76:79], v149 offset:57888
	ds_read_b128 v[178:181], v149 offset:55296
	ds_read_b128 v[182:185], v149 offset:55312
	ds_read_b128 v[186:189], v149 offset:55328
	ds_read_b128 v[190:193], v149 offset:55344
	ds_read_b128 v[194:197], v149 offset:57904
	s_waitcnt lgkmcnt(4)
	v_fma_f32 v68, v65, v178, v68
	v_cndmask_b32_e64 v65, v68, v65, s[10:11]
	v_fma_f32 v68, v179, v65, v69
	v_cndmask_b32_e64 v65, v65, v68, s[12:13]
	v_fma_f32 v68, v180, v65, v70
	v_cndmask_b32_e64 v65, v65, v68, s[14:15]
	v_fmac_f32_e32 v71, v181, v65
	v_cndmask_b32_e64 v65, v71, v65, s[0:1]
	s_waitcnt lgkmcnt(3)
	v_fma_f32 v68, v182, v65, v72
	v_cndmask_b32_e64 v65, v65, v68, s[16:17]
	v_fma_f32 v68, v183, v65, v73
	v_cndmask_b32_e64 v65, v65, v68, s[18:19]
	v_fma_f32 v68, v184, v65, v74
	v_cndmask_b32_e64 v65, v65, v68, s[20:21]
	v_fmac_f32_e32 v75, v185, v65
	v_cndmask_b32_e64 v65, v65, v75, s[38:39]
	s_waitcnt lgkmcnt(2)
	v_fma_f32 v68, v186, v65, v76
	v_cndmask_b32_e64 v65, v65, v68, s[22:23]
	v_fma_f32 v68, v187, v65, v77
	v_cndmask_b32_e64 v65, v65, v68, s[24:25]
	v_fma_f32 v68, v188, v65, v78
	v_cndmask_b32_e64 v65, v65, v68, s[26:27]
	v_fmac_f32_e32 v79, v189, v65
	v_mul_f32_e32 v69, 0xbfb8aa3b, v58
	v_cndmask_b32_e64 v65, v65, v79, s[4:5]
	v_exp_f32_e32 v69, v69
	s_waitcnt lgkmcnt(0)
	v_fma_f32 v68, v190, v65, v194
	v_cndmask_b32_e64 v65, v65, v68, s[28:29]
	v_fma_f32 v68, v191, v65, v195
	v_cndmask_b32_e64 v65, v65, v68, s[30:31]
	v_add_f32_e32 v68, 1.0, v69
	v_rcp_f32_e32 v68, v68
	v_fmac_f32_e32 v196, v192, v65
	v_cndmask_b32_e64 v65, v65, v196, s[34:35]
	v_fmac_f32_e32 v80, v64, v65
	v_mul_f32_e32 v64, 0xbfb8aa3b, v56
	v_mul_f32_e32 v58, v68, v58
	v_exp_f32_e32 v68, v64
	v_mul_f32_e32 v58, v58, v80
	v_add_co_u32_e32 v64, vcc, s40, v66
	v_cvt_pk_bf16_f32 v58, v58, s0
	s_nop 0
	v_addc_co_u32_e32 v65, vcc, 0, v67, vcc
	global_store_short v[64:65], v58, off
	v_add_f32_e32 v58, 1.0, v68
	v_mul_f32_e32 v64, 0xbfb8aa3b, v55
	v_rcp_f32_e32 v58, v58
	v_exp_f32_e32 v64, v64
	v_fmac_f32_e32 v82, v81, v80
	s_mov_b32 s40, 0x2590c000
	v_mul_f32_e32 v56, v58, v56
	v_add_f32_e32 v58, 1.0, v64
	v_rcp_f32_e32 v58, v58
	v_mul_f32_e32 v56, v56, v82
	v_add_co_u32_e32 v64, vcc, s40, v66
	v_cvt_pk_bf16_f32 v56, v56, s0
	s_nop 0
	v_addc_co_u32_e32 v65, vcc, 0, v67, vcc
	v_mul_f32_e32 v55, v58, v55
	s_waitcnt vmcnt(17)
	v_lshlrev_b32_e32 v58, 16, v57
	global_store_short v[64:65], v56, off
	v_mul_f32_e32 v56, 0xbfb8aa3b, v58
	v_exp_f32_e32 v57, v56
	v_fmac_f32_e32 v124, v122, v82
	s_mov_b32 s40, 0x25918000
	v_mul_f32_e32 v55, v55, v124
	v_add_f32_e32 v57, 1.0, v57
	v_rcp_f32_e32 v64, v57
	v_add_co_u32_e32 v56, vcc, s40, v66
	v_cvt_pk_bf16_f32 v55, v55, s0
	s_nop 0
	v_addc_co_u32_e32 v57, vcc, 0, v67, vcc
	global_store_short v[56:57], v55, off
	v_fmac_f32_e32 v63, v126, v124
	v_mul_f32_e32 v55, v64, v58
	v_mul_f32_e32 v55, v55, v63
	s_mov_b64 s[100:101], 0x25924000
	v_lshl_add_u64 v[56:57], v[66:67], 0, s[100:101]
	v_cvt_pk_bf16_f32 v55, v55, s0
	global_store_short v[56:57], v55, off
	s_and_saveexec_b64 s[40:41], s[34:35]
	ds_write_b32 v149, v63 offset:55364
	s_or_b64 exec, exec, s[40:41]
	s_or_b32 s78, s93, 3
	s_cmpk_lt_u32 s78, 0x7f
	s_cselect_b64 s[40:41], -1, 0
	s_cmpk_gt_u32 s78, 0x7e
	s_cbranch_scc1 .LBB0_291
	v_lshlrev_b32_e32 v56, 16, v130
	v_and_b32_e32 v57, 0xffff0000, v130
	v_pk_fma_f32 v[56:57], v[104:105], v[56:57], v[100:101]
	v_lshlrev_b32_e32 v64, 16, v132
	v_and_b32_e32 v65, 0xffff0000, v132
	v_pk_fma_f32 v[56:57], v[106:107], v[64:65], v[56:57]
	v_lshlrev_b32_e32 v68, 16, v134
	v_and_b32_e32 v69, 0xffff0000, v134
	v_pk_fma_f32 v[56:57], v[108:109], v[68:69], v[56:57]
	s_waitcnt vmcnt(19)
	v_lshlrev_b32_e32 v70, 16, v169
	v_and_b32_e32 v71, 0xffff0000, v169
	v_pk_fma_f32 v[56:57], v[110:111], v[70:71], v[56:57]
	s_nop 0
	v_cvt_pk_bf16_f32 v55, v56, v57
	v_pk_fma_f32 v[56:57], v[104:105], v[64:65], v[100:101]
	s_waitcnt vmcnt(18)
	v_lshlrev_b32_e32 v64, 16, v170
	v_pk_fma_f32 v[56:57], v[106:107], v[68:69], v[56:57]
	v_and_b32_e32 v65, 0xffff0000, v170
	v_pk_fma_f32 v[56:57], v[108:109], v[70:71], v[56:57]
	s_nop 0
	v_pk_fma_f32 v[56:57], v[110:111], v[64:65], v[56:57]
	s_nop 0
	v_cvt_pk_bf16_f32 v56, v56, v57
	ds_write2_b32 v123, v55, v56 offset1:72
	v_pk_fma_f32 v[56:57], v[104:105], v[68:69], v[100:101]
	s_waitcnt vmcnt(17)
	v_lshlrev_b32_e32 v68, 16, v171
	v_pk_fma_f32 v[56:57], v[106:107], v[70:71], v[56:57]
	v_and_b32_e32 v69, 0xffff0000, v171
	v_pk_fma_f32 v[56:57], v[108:109], v[64:65], v[56:57]
	s_nop 0
	v_pk_fma_f32 v[56:57], v[110:111], v[68:69], v[56:57]
	s_nop 0
	v_cvt_pk_bf16_f32 v55, v56, v57
	v_pk_fma_f32 v[56:57], v[104:105], v[70:71], v[100:101]
	s_waitcnt vmcnt(16)
	v_lshlrev_b32_e32 v70, 16, v172
	v_pk_fma_f32 v[56:57], v[106:107], v[64:65], v[56:57]
	v_and_b32_e32 v71, 0xffff0000, v172
	v_pk_fma_f32 v[56:57], v[108:109], v[68:69], v[56:57]
	s_nop 0
	v_pk_fma_f32 v[56:57], v[110:111], v[70:71], v[56:57]
	s_nop 0
	v_cvt_pk_bf16_f32 v56, v56, v57
	ds_write2_b32 v123, v55, v56 offset0:144 offset1:216
	v_pk_fma_f32 v[56:57], v[104:105], v[64:65], v[100:101]
	s_waitcnt vmcnt(15)
	v_lshlrev_b32_e32 v64, 16, v173
	v_pk_fma_f32 v[56:57], v[106:107], v[68:69], v[56:57]
	v_and_b32_e32 v65, 0xffff0000, v173
	v_pk_fma_f32 v[56:57], v[108:109], v[70:71], v[56:57]
	s_nop 0
	v_pk_fma_f32 v[56:57], v[110:111], v[64:65], v[56:57]
	s_nop 0
	v_cvt_pk_bf16_f32 v55, v56, v57
	v_pk_fma_f32 v[56:57], v[104:105], v[68:69], v[100:101]
	s_waitcnt vmcnt(14)
	v_lshlrev_b32_e32 v68, 16, v174
	v_pk_fma_f32 v[56:57], v[106:107], v[70:71], v[56:57]
	v_and_b32_e32 v69, 0xffff0000, v174
	v_pk_fma_f32 v[56:57], v[108:109], v[64:65], v[56:57]
	s_nop 0
	v_pk_fma_f32 v[56:57], v[110:111], v[68:69], v[56:57]
	s_nop 0
	v_cvt_pk_bf16_f32 v56, v56, v57
	ds_write2_b32 v54, v55, v56 offset0:32 offset1:104
	v_pk_fma_f32 v[56:57], v[104:105], v[70:71], v[100:101]
	s_waitcnt vmcnt(13)
	v_lshlrev_b32_e32 v70, 16, v175
	v_pk_fma_f32 v[56:57], v[106:107], v[64:65], v[56:57]
	v_and_b32_e32 v71, 0xffff0000, v175
	v_pk_fma_f32 v[56:57], v[108:109], v[68:69], v[56:57]
	s_nop 0
	v_pk_fma_f32 v[56:57], v[110:111], v[70:71], v[56:57]
	s_nop 0
	v_cvt_pk_bf16_f32 v55, v56, v57
	v_pk_fma_f32 v[56:57], v[104:105], v[64:65], v[100:101]
	s_waitcnt vmcnt(12)
	v_lshlrev_b32_e32 v64, 16, v176
	v_pk_fma_f32 v[56:57], v[106:107], v[68:69], v[56:57]
	v_and_b32_e32 v65, 0xffff0000, v176
	v_pk_fma_f32 v[56:57], v[108:109], v[70:71], v[56:57]
	s_nop 0
	v_pk_fma_f32 v[56:57], v[110:111], v[64:65], v[56:57]
	s_nop 0
	v_cvt_pk_bf16_f32 v56, v56, v57
	ds_write2_b32 v54, v55, v56 offset0:176 offset1:248

; #define LAS __attribute__((address_space(3)))
; DI float bf2f(unsigned h) { return __uint_as_float(h << 16); }
; DI float fexp2(float x) { return __builtin_amdgcn_exp2f(x); }
; DI float fsigmoid(float x) { return frcp(1.0f + fexp2(-LOG2E * x)); }
; #define LDS_BAR() do { asm volatile("s_waitcnt lgkmcnt(0)" ::: "memory"); __builtin_amdgcn_s_barrier(); asm volatile("" ::: "memory"); } while (0)
; DI void cv_issue_q(const CvJob& j, int idx, int lane, f32x4 (&v)[4], int r0) {
;     const float* W; int K, N, item; bf16* WT; const float* ks; cv_decode(j, idx, W, K, N, WT, ks, item);
;     const int nblk = N / 64, kb = item / nblk, nb = item % nblk, k0 = 64 * kb, n0 = 64 * nb, q = lane >> 4, c16 = lane & 15;
;     const char* ub = (const char*)(W + (size_t)(k0 + r0) * N + n0);
;     const unsigned vo = (unsigned)((16 * q) * N + 4 * c16) * 4u;
; #pragma unroll
;     for (int i = 0; i < 4; ++i) v[i] = *(const f32x4*)(ub + (size_t)i * N * 4 + vo);
; DI void rglru_scan_unit(Frame& F, const Mix0Args& a, int u) {
;     ...
;         { bf16x8 xf[4], waf[4], wxf[4]; unsigned xcr[4];
; #pragma unroll
;           for (int ks = 0; ks < 4; ++ks) { xf[ks] = *(const LAS bf16x8*)(XCc + (l0_ + fr) * S128 + ks * 64 + fq * 16);
;               waf[ks] = *(const LAS bf16x8*)(WAT + (16 * jtile + fr) * S128 + ks * 64 + fq * 16); wxf[ks] = *(const LAS bf16x8*)(WXT + (16 * jtile + fr) * S128 + ks * 64 + fq * 16); }
; #pragma unroll
;           for (int r = 0; r < 4; ++r) xcr[r] = *(const LAS unsigned short*)(XCc + (l0_ + 4 * fq + r) * S128 + (qq * 32 + jj) * 2);
;           f32x4 R = zero4, I = zero4;
; #pragma unroll
;           for (int ks = 0; ks < 4; ++ks) { R = __builtin_amdgcn_mfma_f32_16x16x32_bf16(xf[ks], waf[ks], R, 0, 0, 0); I = __builtin_amdgcn_mfma_f32_16x16x32_bf16(xf[ks], wxf[ks], I, 0, 0, 0); }
; #pragma unroll
;           for (int r = 0; r < 4; ++r) {
;               const float rr = fsigmoid(R[r] + bav), ig = fsigmoid(I[r] + bxv);
;               const float aa = fexp2(-sp8l2 * rr); const float om = __builtin_fmaf(-aa, aa, 1.0f);
;               av[r] = aa; uv[r] = __builtin_sqrtf(om) * (ig * bf2f(xcr[r]));
;               Hseg = aa * Hseg + uv[r]; Aseg *= aa; } }
;         const int sgi = ltile * 4 + fq;
;         SEGA[jj * 20 + sgi] = Aseg; SEGH[jj * 20 + sgi] = Hseg;
;         LDS_BAR();
.LBB0_302:
	s_lshr_b32 s41, s40, 6
	v_cvt_f32_u32_e32 v50, s41
	s_sub_i32 s84, 0, s41
	s_abs_i32 s79, s87
	s_ashr_i32 s78, s87, 31
	v_rcp_iflag_f32_e32 v50, v50
	v_mul_u32_u24_e32 v76, s40, v102
	v_or_b32_e32 v80, v76, v125
	v_lshlrev_b32_e32 v82, 2, v80
	v_mul_f32_e32 v50, 0x4f7ffffe, v50
	v_cvt_u32_f32_e32 v50, v50
	v_lshlrev_b32_e32 v71, 16, v71
	v_lshlrev_b32_e32 v69, 16, v69
	ds_read_b128 v[54:57], v103 offset:36864
	v_readfirstlane_b32 s88, v50
	ds_read_b128 v[50:53], v164 offset:18432
	s_mul_i32 s84, s84, s88
	s_mul_hi_u32 s84, s88, s84
	s_add_i32 s88, s88, s84
	s_mul_hi_u32 s84, s79, s88
	s_mul_i32 s88, s84, s41
	s_sub_i32 s79, s79, s88
	s_add_i32 s89, s84, 1
	s_sub_i32 s88, s79, s41
	s_cmp_ge_u32 s79, s41
	ds_read_b128 v[58:61], v103 offset:46080
	ds_read_b128 v[62:65], v164 offset:18496
	ds_read_b128 v[72:75], v103 offset:36928
	ds_read_b128 v[76:79], v103 offset:46144
	ds_read_b128 v[182:185], v164 offset:18560
	s_cselect_b32 s84, s89, s84
	s_waitcnt lgkmcnt(5)
	v_mfma_f32_16x16x32_bf16 v[54:57], v[50:53], v[54:57], 0
	s_cselect_b32 s79, s88, s79
	s_add_i32 s88, s84, 1
	s_cmp_ge_u32 s79, s41
	s_cselect_b32 s79, s88, s84
	s_waitcnt lgkmcnt(4)
	v_mfma_f32_16x16x32_bf16 v[50:53], v[50:53], v[58:61], 0
	s_xor_b32 s79, s79, s78
	s_sub_i32 s78, s79, s78
	s_mul_i32 s41, s78, s41
	s_waitcnt lgkmcnt(2)
	v_mfma_f32_16x16x32_bf16 v[54:57], v[62:65], v[72:75], v[54:57]
	ds_read_b128 v[58:61], v103 offset:36992
	ds_read_b128 v[72:75], v164 offset:18624
	s_lshl_b32 s78, s78, 6
	s_or_b32 s79, s78, 12
	s_waitcnt lgkmcnt(3)
	v_mfma_f32_16x16x32_bf16 v[50:53], v[62:65], v[76:79], v[50:53]
	ds_read_b128 v[76:79], v103 offset:37056
	s_sub_i32 s41, s87, s41
	s_mul_hi_i32 s89, s79, s40
	s_mul_i32 s88, s79, s40
	s_waitcnt lgkmcnt(2)
	v_mfma_f32_16x16x32_bf16 v[54:57], v[182:185], v[58:61], v[54:57]
	s_lshl_b32 s78, s41, 6
	s_lshl_b64 s[88:89], s[88:89], 2
	s_add_u32 s41, s36, s88
	s_addc_u32 s84, s37, s89
	s_ashr_i32 s79, s78, 31
	s_lshl_b64 s[36:37], s[78:79], 2
	s_waitcnt lgkmcnt(0)
	v_mfma_f32_16x16x32_bf16 v[76:79], v[72:75], v[76:79], v[54:57]
	s_add_u32 s36, s41, s36
	s_addc_u32 s37, s84, s37
	s_lshl_b32 s96, s40, 2
	v_lshl_add_u64 v[80:81], s[36:37], 0, v[82:83]
	v_lshl_add_u64 v[62:63], v[80:81], 0, s[96:97]
	s_nop 2
	v_add_f32_e32 v54, v165, v76
	v_lshl_add_u64 v[80:81], v[62:63], 0, s[96:97]
	global_load_dwordx4 v[58:61], v[62:63], off nt
	s_nop 0
	global_load_dwordx4 v[62:65], v[80:81], off nt
	ds_read_b128 v[186:189], v103 offset:46208
	ds_read_b128 v[190:193], v103 offset:46272
	v_mul_f32_e32 v54, 0xbfb8aa3b, v54
	v_exp_f32_e32 v54, v54
	s_waitcnt lgkmcnt(1)
	v_mfma_f32_16x16x32_bf16 v[182:185], v[182:185], v[186:189], v[50:53]
	v_lshl_add_u64 v[80:81], v[80:81], 0, s[96:97]
	v_add_f32_e32 v77, v165, v77
	s_nop 0
	v_add_f32_e32 v50, 1.0, v54
	v_rcp_f32_e32 v76, v50
	global_load_dwordx4 v[54:57], v82, s[36:37] nt
	global_load_dwordx4 v[50:53], v[80:81], off nt
	s_waitcnt lgkmcnt(0)
	v_mfma_f32_16x16x32_bf16 v[72:75], v[72:75], v[190:193], v[182:185]
	v_mul_f32_e32 v77, 0xbfb8aa3b, v77
	v_mul_f32_e64 v76, v76, -v168
	v_exp_f32_e32 v82, v76
	v_exp_f32_e32 v77, v77
	ds_read_u16 v81, v177 offset:18432
	ds_read_u16 v122, v177 offset:18720
	ds_read_u16 v124, v177 offset:19008
	ds_read_u16 v126, v177 offset:19296
	v_add_f32_e32 v72, v167, v72
	v_fma_f32 v76, -v82, v82, 1.0
	s_nop 0
	s_nop 0
	v_mul_f32_e32 v72, 0xbfb8aa3b, v72
	v_exp_f32_e32 v72, v72
	s_nop 0
	v_sqrt_f32_e32 v80, v76
	v_add_f32_e32 v77, 1.0, v77
	v_add_f32_e32 v72, 1.0, v72
	v_rcp_f32_e32 v72, v72
	v_add_u32_e32 v128, -1, v80
	v_fma_f32 v182, -v128, v80, v76
	v_cmp_ge_f32_e64 s[36:37], 0, v182
	v_add_u32_e32 v182, 1, v80
	v_rcp_f32_e32 v77, v77
	v_cndmask_b32_e64 v128, v80, v128, s[36:37]
	v_fma_f32 v80, -v182, v80, v76
	v_cmp_lt_f32_e64 s[36:37], 0, v80
	v_add_f32_e32 v78, v165, v78
	v_mul_f32_e32 v78, 0xbfb8aa3b, v78
	v_cndmask_b32_e64 v80, v128, v182, s[36:37]
	s_nop 0
	s_nop 0
	s_nop 0
	v_exp_f32_e32 v78, v78
	v_add_f32_e32 v74, v167, v74
	v_mov_b32_e32 v76, v80
	s_waitcnt lgkmcnt(3)
	v_lshlrev_b32_e32 v80, 16, v81
	v_mul_f32_e32 v72, v72, v80
	v_mul_f32_e32 v128, v72, v76
	v_mul_f32_e64 v72, v77, -v168
	v_exp_f32_e32 v206, v72
	v_add_f32_e32 v72, v167, v73
	v_mul_f32_e32 v72, 0xbfb8aa3b, v72
	v_exp_f32_e32 v72, v72
	v_fma_f32 v73, -v206, v206, 1.0
	s_nop 0
	s_nop 0
	v_add_f32_e32 v72, 1.0, v72
	v_add_f32_e32 v78, 1.0, v78
	s_nop 0
	v_sqrt_f32_e32 v76, v73
	v_rcp_f32_e32 v72, v72
	v_rcp_f32_e32 v78, v78
	v_fma_f32 v77, 0, v82, v128
	v_add_u32_e32 v80, -1, v76
	v_fma_f32 v81, -v80, v76, v73
	v_cmp_ge_f32_e64 s[36:37], 0, v81
	v_add_u32_e32 v81, 1, v76
	v_mul_f32_e32 v74, 0xbfb8aa3b, v74
	v_cndmask_b32_e64 v80, v76, v80, s[36:37]
	v_fma_f32 v76, -v81, v76, v73
	v_cmp_lt_f32_e64 s[36:37], 0, v76
	v_exp_f32_e32 v74, v74
	v_add_f32_e32 v79, v165, v79
	v_cndmask_b32_e64 v76, v80, v81, s[36:37]
	s_nop 0
	s_nop 0
	s_nop 0
	v_mul_f32_e32 v79, 0xbfb8aa3b, v79
	v_exp_f32_e32 v79, v79
	v_mov_b32_e32 v73, v76
	s_waitcnt lgkmcnt(2)
	v_lshlrev_b32_e32 v76, 16, v122
	v_mul_f32_e32 v72, v72, v76
	v_mul_f32_e64 v76, v78, -v168
	v_exp_f32_e32 v122, v76
	v_mul_f32_e32 v73, v72, v73
	v_fma_f32 v72, v206, v77, v73
	v_add_f32_e32 v74, 1.0, v74
	v_fma_f32 v76, -v122, v122, 1.0
	s_nop 0
	s_nop 0
	v_rcp_f32_e32 v74, v74
	v_add_f32_e32 v79, 1.0, v79
	s_nop 0
	v_sqrt_f32_e32 v77, v76
	v_rcp_f32_e32 v79, v79
	v_mul_f32_e32 v78, v82, v206
	v_add_u32_e32 v80, -1, v77
	v_fma_f32 v81, -v80, v77, v76
	v_cmp_ge_f32_e64 s[36:37], 0, v81
	v_add_u32_e32 v81, 1, v77
	s_nop 0
	v_cndmask_b32_e64 v80, v77, v80, s[36:37]
	v_fma_f32 v77, -v81, v77, v76
	v_cmp_lt_f32_e64 s[36:37], 0, v77
	s_nop 1
	v_cndmask_b32_e64 v77, v80, v81, s[36:37]
	s_nop 0
	s_nop 0
	s_nop 0
	s_nop 1
	v_mov_b32_e32 v76, v77
	s_waitcnt lgkmcnt(1)
	v_lshlrev_b32_e32 v77, 16, v124
	v_mul_f32_e32 v74, v74, v77
	v_mul_f32_e32 v124, v74, v76
	v_fma_f32 v74, v122, v72, v124
	v_mul_f32_e64 v72, v79, -v168
	v_exp_f32_e32 v207, v72
	v_add_f32_e32 v72, v167, v75
	v_mul_f32_e32 v72, 0xbfb8aa3b, v72
	v_exp_f32_e32 v72, v72
	v_fma_f32 v75, -v207, v207, 1.0
	s_nop 0
	s_nop 0
	v_mul_f32_e32 v77, v122, v78
	v_add_f32_e32 v72, 1.0, v72
	s_nop 0
	v_sqrt_f32_e32 v76, v75
	v_rcp_f32_e32 v72, v72
	v_add_u32_e32 v78, -1, v76
	v_fma_f32 v79, -v78, v76, v75
	v_cmp_ge_f32_e64 s[36:37], 0, v79
	v_add_u32_e32 v79, 1, v76
	s_nop 0
	v_cndmask_b32_e64 v78, v76, v78, s[36:37]
	v_fma_f32 v76, -v79, v76, v75
	v_cmp_lt_f32_e64 s[36:37], 0, v76
	s_nop 1
	v_cndmask_b32_e64 v76, v78, v79, s[36:37]
	s_nop 0
	s_nop 0
	s_nop 0
	s_mov_b32 s36, 0x25c00000
	s_nop 0
	v_mov_b32_e32 v75, v76
	s_waitcnt lgkmcnt(0)
	v_lshlrev_b32_e32 v76, 16, v126
	v_mul_f32_e32 v72, v72, v76
	v_mul_f32_e32 v72, v72, v75
	v_fma_f32 v74, v207, v74, v72
	v_mul_f32_e32 v75, v207, v77
	ds_write2st64_b32 v150, v75, v74 offset0:236 offset1:246
	s_waitcnt lgkmcnt(0)
	s_barrier
; #define LAS __attribute__((address_space(3)))
; DI float bf2f(unsigned h) { return __uint_as_float(h << 16); }
; DI unsigned pk2(float lo, float hi) { f32x2 v = {lo, hi}; bf16v2 b = __builtin_convertvector(v, bf16v2); return __builtin_bit_cast(unsigned, b); }
; DI float fsilu(float x) { return x * fsigmoid(x); }
; DI void rglru_scan_unit(Frame& F, const Mix0Args& a, int u) {
;     ...
;         float carry = HPREV[jj * 20 + (n & 1)]; float sa[15], sh[15];
;         { f32x4 a4[4], h4[4];
; #pragma unroll
;           for (int i = 0; i < 4; ++i) { a4[i] = *(const LAS f32x4*)(SEGA + jj * 20 + 4 * i); h4[i] = *(const LAS f32x4*)(SEGH + jj * 20 + 4 * i); }
; #pragma unroll
;           for (int s = 0; s < 15; ++s) { sa[s] = a4[s >> 2][s & 3]; sh[s] = h4[s >> 2][s & 3]; } }
; #pragma unroll
;         for (int s = 0; s < 15; ++s) carry = (s < sgi) ? sa[s] * carry + sh[s] : carry;
; #pragma unroll
;         for (int r = 0; r < 4; ++r) { carry = av[r] * carry + uv[r];
;             const float o = carry * fsilu(bf2f(gb_cur[r]));
;             obcol[(row0 + l0_ + 4 * fq + r) * a.out_ld] = (bf16)(pk2(o, 0.f) & 0xffffu); }
;         if (sgi == 15) HPREV[jj * 20 + ((n + 1) & 1)] = carry;
	ds_read_b32 v126, v149 offset:55364
	ds_read_b128 v[74:77], v149 offset:60416
	ds_read_b128 v[78:81], v149 offset:62976
	ds_read_b128 v[182:185], v149 offset:60432
	ds_read_b128 v[186:189], v149 offset:60448
	ds_read_b128 v[190:193], v149 offset:62992
	ds_read_b128 v[194:197], v149 offset:63008
	ds_read_b128 v[198:201], v149 offset:60464
	ds_read_b128 v[202:205], v149 offset:63024
	s_waitcnt lgkmcnt(6)
	v_fma_f32 v74, v126, v74, v78
	v_cndmask_b32_e64 v74, v74, v126, s[10:11]
	v_fma_f32 v75, v75, v74, v79
	v_cndmask_b32_e64 v74, v74, v75, s[12:13]
	v_fma_f32 v75, v76, v74, v80
	v_cndmask_b32_e64 v74, v74, v75, s[14:15]
	v_fmac_f32_e32 v81, v77, v74
	v_cndmask_b32_e64 v74, v81, v74, s[0:1]
	s_waitcnt lgkmcnt(3)
	v_fma_f32 v75, v182, v74, v190
	v_cndmask_b32_e64 v74, v74, v75, s[16:17]
	v_fma_f32 v75, v183, v74, v191
	v_cndmask_b32_e64 v74, v74, v75, s[18:19]
	v_fma_f32 v75, v184, v74, v192
	v_cndmask_b32_e64 v74, v74, v75, s[20:21]
	v_fmac_f32_e32 v193, v185, v74
	v_cndmask_b32_e64 v74, v74, v193, s[38:39]
	s_waitcnt lgkmcnt(2)
	v_fma_f32 v75, v186, v74, v194
	v_cndmask_b32_e64 v74, v74, v75, s[22:23]
	v_fma_f32 v75, v187, v74, v195
	v_cndmask_b32_e64 v74, v74, v75, s[24:25]
	v_fma_f32 v75, v188, v74, v196
	v_cndmask_b32_e64 v74, v74, v75, s[26:27]
	v_fmac_f32_e32 v197, v189, v74
	v_mul_f32_e32 v76, 0xbfb8aa3b, v71
	v_cndmask_b32_e64 v74, v74, v197, s[4:5]
	v_exp_f32_e32 v76, v76
	s_waitcnt lgkmcnt(0)
	v_fma_f32 v75, v198, v74, v202
	v_cndmask_b32_e64 v74, v74, v75, s[28:29]
	v_fma_f32 v75, v199, v74, v203
	v_cndmask_b32_e64 v74, v74, v75, s[30:31]
	v_add_f32_e32 v75, 1.0, v76
	v_rcp_f32_e32 v75, v75
	v_fmac_f32_e32 v204, v200, v74
	v_cndmask_b32_e64 v74, v74, v204, s[34:35]
	v_fmac_f32_e32 v128, v82, v74
	v_mul_f32_e32 v71, v75, v71
	v_lshlrev_b32_e32 v75, 16, v70
	v_mul_f32_e32 v70, 0xbfb8aa3b, v75
	v_exp_f32_e32 v76, v70
	v_mul_f32_e32 v71, v71, v128
	v_add_co_u32_e32 v70, vcc, s36, v66
	v_cvt_pk_bf16_f32 v74, v71, s0
	s_nop 0
	v_addc_co_u32_e32 v71, vcc, 0, v67, vcc
	global_store_short v[70:71], v74, off
	v_add_f32_e32 v70, 1.0, v76
	v_rcp_f32_e32 v70, v70
	v_mul_f32_e32 v71, 0xbfb8aa3b, v69
	v_exp_f32_e32 v71, v71
	v_fmac_f32_e32 v73, v206, v128
	v_mul_f32_e32 v70, v70, v75
	v_mul_f32_e32 v70, v70, v73
	v_cvt_pk_bf16_f32 v74, v70, s0
	v_add_f32_e32 v70, 1.0, v71
	s_mov_b32 s36, 0x25c0c000
	v_rcp_f32_e32 v75, v70
	v_add_co_u32_e32 v70, vcc, s36, v66
	v_fmac_f32_e32 v124, v122, v73
	s_nop 0
	v_addc_co_u32_e32 v71, vcc, 0, v67, vcc
	global_store_short v[70:71], v74, off
	v_lshlrev_b32_e32 v70, 16, v68
	v_mul_f32_e32 v68, 0xbfb8aa3b, v70
	v_exp_f32_e32 v71, v68
	v_mul_f32_e32 v69, v75, v69
	v_mul_f32_e32 v69, v69, v124
	v_cvt_pk_bf16_f32 v73, v69, s0
	v_add_f32_e32 v69, 1.0, v71
	v_rcp_f32_e32 v71, v69
	s_mov_b32 s36, 0x25c18000
	v_add_co_u32_e32 v68, vcc, s36, v66
	v_fmac_f32_e32 v72, v207, v124
	s_nop 0
	v_addc_co_u32_e32 v69, vcc, 0, v67, vcc
	global_store_short v[68:69], v73, off
	v_mul_f32_e32 v68, v71, v70
	v_mul_f32_e32 v68, v68, v72
	s_mov_b64 s[100:101], 0x25c24000
	v_lshl_add_u64 v[66:67], v[66:67], 0, s[100:101]
	v_cvt_pk_bf16_f32 v68, v68, s0
	global_store_short v[66:67], v68, off
	s_and_saveexec_b64 s[36:37], s[34:35]
	s_cbranch_execz .LBB0_248
	ds_write_b32 v149, v72 offset:55360
	s_branch .LBB0_248
